# row sum-of-squares exchange in P2/P7/P9 epilogues: v_permlane16/32_swap instead of ds_bpermute round trips, stacked on v66
# speedup vs baseline: 1.0004x; 1.0004x over previous
.LBB0_409:
	s_or_b64 exec, exec, s[46:47]
	s_lshr_b32 s2, s54, 2
	s_and_b32 s33, s54, 3
	v_mov_b32_e32 v130, v0
	s_lshl_b32 s9, s2, 4
	s_lshl_b32 s11, s33, 1
	s_barrier
	s_or_b32 s12, s9, s11
	v_ashrrev_i32_e32 v131, 31, v130
	s_ashr_i32 s9, s8, 31
	v_lshl_add_u64 v[130:131], v[130:131], 4, s[62:63]
	s_or_b32 s40, s12, 8
	s_lshl_b64 s[14:15], s[8:9], 17
	s_mov_b32 s13, s41
	s_lshl_b64 s[46:47], s[40:41], 12
	v_lshl_add_u64 v[132:133], v[130:131], 0, s[14:15]
	s_lshl_b64 s[48:49], s[12:13], 12
	s_or_b32 s40, s12, 1
	v_lshl_add_u64 v[134:135], v[132:133], 0, s[48:49]
	s_add_u32 s50, s48, 8
	s_addc_u32 s51, s49, 0
	s_or_b32 s40, s12, 9
	s_or_b32 s12, s8, 1
	global_load_dwordx2 v[156:157], v[134:135], off sc1
	v_lshl_add_u64 v[134:135], v[132:133], 0, s[50:51]
	s_add_u32 s66, s46, 8
	s_addc_u32 s67, s47, 0
	s_ashr_i32 s13, s12, 31
	global_load_dwordx2 v[158:159], v[134:135], off sc1
	v_lshl_add_u64 v[134:135], v[132:133], 0, s[46:47]
	v_lshl_add_u64 v[132:133], v[132:133], 0, s[66:67]
	s_lshl_b64 s[12:13], s[12:13], 17
	global_load_dwordx2 v[160:161], v[134:135], off sc1
	global_load_dwordx2 v[162:163], v[132:133], off sc1
	v_lshl_add_u64 v[132:133], v[130:131], 0, s[12:13]
	v_lshl_add_u64 v[134:135], v[132:133], 0, s[48:49]
	s_or_b32 s12, s8, 2
	global_load_dwordx2 v[164:165], v[134:135], off sc1
	v_lshl_add_u64 v[134:135], v[132:133], 0, s[50:51]
	s_ashr_i32 s13, s12, 31
	global_load_dwordx2 v[166:167], v[134:135], off sc1
	v_lshl_add_u64 v[134:135], v[132:133], 0, s[46:47]
	v_lshl_add_u64 v[132:133], v[132:133], 0, s[66:67]
	s_lshl_b64 s[12:13], s[12:13], 17
	global_load_dwordx2 v[168:169], v[134:135], off sc1
	global_load_dwordx2 v[170:171], v[132:133], off sc1
	v_lshl_add_u64 v[132:133], v[130:131], 0, s[12:13]
	v_lshl_add_u64 v[134:135], v[132:133], 0, s[48:49]
	s_or_b32 s12, s8, 3
	global_load_dwordx2 v[172:173], v[134:135], off sc1
	v_lshl_add_u64 v[134:135], v[132:133], 0, s[50:51]
	s_ashr_i32 s13, s12, 31
	global_load_dwordx2 v[174:175], v[134:135], off sc1
	v_lshl_add_u64 v[134:135], v[132:133], 0, s[46:47]
	v_lshl_add_u64 v[132:133], v[132:133], 0, s[66:67]
	s_lshl_b64 s[12:13], s[12:13], 17
	global_load_dwordx2 v[176:177], v[134:135], off sc1
	global_load_dwordx2 v[178:179], v[132:133], off sc1
	v_lshl_add_u64 v[132:133], v[130:131], 0, s[12:13]
	v_lshl_add_u64 v[134:135], v[132:133], 0, s[48:49]
	s_or_b32 s12, s8, 4
	global_load_dwordx2 v[180:181], v[134:135], off sc1
	v_lshl_add_u64 v[134:135], v[132:133], 0, s[50:51]
	s_ashr_i32 s13, s12, 31
	global_load_dwordx2 v[182:183], v[134:135], off sc1
	v_lshl_add_u64 v[134:135], v[132:133], 0, s[46:47]
	v_lshl_add_u64 v[132:133], v[132:133], 0, s[66:67]
	s_lshl_b64 s[12:13], s[12:13], 17
	global_load_dwordx2 v[184:185], v[134:135], off sc1
	global_load_dwordx2 v[196:197], v[132:133], off sc1
	v_lshl_add_u64 v[132:133], v[130:131], 0, s[12:13]
	v_lshl_add_u64 v[134:135], v[132:133], 0, s[48:49]
	global_load_dwordx2 v[198:199], v[134:135], off sc1
	v_lshl_add_u64 v[134:135], v[132:133], 0, s[50:51]
	global_load_dwordx2 v[200:201], v[134:135], off sc1
	v_lshl_add_u64 v[134:135], v[132:133], 0, s[46:47]
	global_load_dwordx2 v[202:203], v[134:135], off sc1
	s_or_b32 s12, s8, 5
	s_ashr_i32 s13, s12, 31
	v_lshl_add_u64 v[132:133], v[132:133], 0, s[66:67]
	s_lshl_b64 s[12:13], s[12:13], 17
	global_load_dwordx2 v[152:153], v[132:133], off sc1
	v_lshl_add_u64 v[132:133], v[130:131], 0, s[12:13]
	v_lshl_add_u64 v[134:135], v[132:133], 0, s[48:49]
	global_load_dwordx2 v[154:155], v[134:135], off sc1
	v_lshl_add_u64 v[134:135], v[132:133], 0, s[50:51]
	global_load_dwordx2 v[150:151], v[134:135], off sc1
	v_lshl_add_u64 v[134:135], v[132:133], 0, s[46:47]
	global_load_dwordx2 v[148:149], v[134:135], off sc1
	s_or_b32 s12, s8, 6
	s_ashr_i32 s13, s12, 31
	v_lshl_add_u64 v[132:133], v[132:133], 0, s[66:67]
	s_lshl_b64 s[12:13], s[12:13], 17
	global_load_dwordx2 v[144:145], v[132:133], off sc1
	v_lshl_add_u64 v[132:133], v[130:131], 0, s[12:13]
	v_lshl_add_u64 v[134:135], v[132:133], 0, s[48:49]
	s_or_b32 s8, s8, 7
	global_load_dwordx2 v[146:147], v[134:135], off sc1
	v_lshl_add_u64 v[134:135], v[132:133], 0, s[50:51]
	s_ashr_i32 s9, s8, 31
	global_load_dwordx2 v[142:143], v[134:135], off sc1
	v_lshl_add_u64 v[134:135], v[132:133], 0, s[46:47]
	s_lshl_b64 s[8:9], s[8:9], 17
	s_lshl_b32 s11, s76, 8
	s_waitcnt vmcnt(25)
	v_lshlrev_b32_e32 v204, 16, v156
	v_and_b32_e32 v205, 0xffff0000, v156
	v_lshlrev_b32_e32 v156, 16, v157
	v_and_b32_e32 v157, 0xffff0000, v157
	v_pk_add_f32 v[156:157], v[156:157], 0 op_sel_hi:[1,0]
	s_waitcnt vmcnt(24)
	v_lshlrev_b32_e32 v206, 16, v158
	v_and_b32_e32 v207, 0xffff0000, v158
	v_lshlrev_b32_e32 v158, 16, v159
	v_and_b32_e32 v159, 0xffff0000, v159
	v_pk_add_f32 v[158:159], v[158:159], 0 op_sel_hi:[1,0]
	s_waitcnt vmcnt(23)
	v_lshlrev_b32_e32 v208, 16, v160
	v_and_b32_e32 v209, 0xffff0000, v160
	v_lshlrev_b32_e32 v160, 16, v161
	s_waitcnt vmcnt(21)
	v_lshlrev_b32_e32 v222, 16, v164
	v_and_b32_e32 v223, 0xffff0000, v164
	v_lshlrev_b32_e32 v164, 16, v165
	v_and_b32_e32 v165, 0xffff0000, v165
	v_and_b32_e32 v161, 0xffff0000, v161
	v_pk_add_f32 v[156:157], v[156:157], v[164:165]
	s_waitcnt vmcnt(20)
	v_lshlrev_b32_e32 v164, 16, v166
	v_and_b32_e32 v165, 0xffff0000, v166
	v_lshlrev_b32_e32 v166, 16, v167
	v_and_b32_e32 v167, 0xffff0000, v167
	v_pk_add_f32 v[160:161], v[160:161], 0 op_sel_hi:[1,0]
	v_lshlrev_b32_e32 v210, 16, v162
	v_and_b32_e32 v211, 0xffff0000, v162
	v_lshlrev_b32_e32 v162, 16, v163
	v_and_b32_e32 v163, 0xffff0000, v163
	v_pk_add_f32 v[158:159], v[158:159], v[166:167]
	s_waitcnt vmcnt(19)
	v_lshlrev_b32_e32 v166, 16, v168
	v_and_b32_e32 v167, 0xffff0000, v168
	v_lshlrev_b32_e32 v168, 16, v169
	v_and_b32_e32 v169, 0xffff0000, v169
	v_pk_add_f32 v[162:163], v[162:163], 0 op_sel_hi:[1,0]
	v_pk_add_f32 v[160:161], v[160:161], v[168:169]
	s_waitcnt vmcnt(18)
	v_lshlrev_b32_e32 v168, 16, v170
	v_and_b32_e32 v169, 0xffff0000, v170
	v_lshlrev_b32_e32 v170, 16, v171
	v_and_b32_e32 v171, 0xffff0000, v171
	v_pk_add_f32 v[162:163], v[162:163], v[170:171]
	s_waitcnt vmcnt(17)
	v_lshlrev_b32_e32 v170, 16, v172
	v_and_b32_e32 v171, 0xffff0000, v172
	v_lshlrev_b32_e32 v172, 16, v173
	v_and_b32_e32 v173, 0xffff0000, v173
	v_pk_add_f32 v[156:157], v[156:157], v[172:173]
	s_waitcnt vmcnt(16)
	v_lshlrev_b32_e32 v172, 16, v174
	v_and_b32_e32 v173, 0xffff0000, v174
	v_lshlrev_b32_e32 v174, 16, v175
	v_and_b32_e32 v175, 0xffff0000, v175
	v_pk_add_f32 v[206:207], v[206:207], 0 op_sel_hi:[1,0]
	v_pk_add_f32 v[158:159], v[158:159], v[174:175]
	s_waitcnt vmcnt(15)
	v_lshlrev_b32_e32 v174, 16, v177
	v_and_b32_e32 v175, 0xffff0000, v177
	v_pk_add_f32 v[208:209], v[208:209], 0 op_sel_hi:[1,0]
	v_pk_add_f32 v[164:165], v[206:207], v[164:165]
	v_pk_add_f32 v[160:161], v[160:161], v[174:175]
	s_waitcnt vmcnt(14)
	v_lshlrev_b32_e32 v174, 16, v179
	v_and_b32_e32 v175, 0xffff0000, v179
	v_pk_add_f32 v[204:205], v[204:205], 0 op_sel_hi:[1,0]
	v_pk_add_f32 v[210:211], v[210:211], 0 op_sel_hi:[1,0]
	v_pk_add_f32 v[166:167], v[208:209], v[166:167]
	v_pk_add_f32 v[164:165], v[164:165], v[172:173]
	v_lshlrev_b32_e32 v172, 16, v176
	v_and_b32_e32 v173, 0xffff0000, v176
	v_pk_add_f32 v[162:163], v[162:163], v[174:175]
	s_waitcnt vmcnt(13)
	v_lshlrev_b32_e32 v174, 16, v181
	v_and_b32_e32 v175, 0xffff0000, v181
	v_pk_add_f32 v[204:205], v[204:205], v[222:223]
	v_pk_add_f32 v[168:169], v[210:211], v[168:169]
	v_pk_add_f32 v[166:167], v[166:167], v[172:173]
	v_lshlrev_b32_e32 v172, 16, v178
	v_and_b32_e32 v173, 0xffff0000, v178
	v_pk_add_f32 v[156:157], v[156:157], v[174:175]
	s_waitcnt vmcnt(12)
	v_lshlrev_b32_e32 v174, 16, v183
	v_and_b32_e32 v175, 0xffff0000, v183
	v_pk_add_f32 v[170:171], v[204:205], v[170:171]
	v_pk_add_f32 v[168:169], v[168:169], v[172:173]
	v_lshlrev_b32_e32 v172, 16, v180
	v_and_b32_e32 v173, 0xffff0000, v180
	v_pk_add_f32 v[158:159], v[158:159], v[174:175]
	s_waitcnt vmcnt(11)
	v_lshlrev_b32_e32 v174, 16, v185
	v_and_b32_e32 v175, 0xffff0000, v185
	v_pk_add_f32 v[170:171], v[170:171], v[172:173]
	v_lshlrev_b32_e32 v172, 16, v182
	v_and_b32_e32 v173, 0xffff0000, v182
	v_pk_add_f32 v[160:161], v[160:161], v[174:175]
	s_waitcnt vmcnt(10)
	v_lshlrev_b32_e32 v174, 16, v197
	v_and_b32_e32 v175, 0xffff0000, v197
	v_pk_add_f32 v[164:165], v[164:165], v[172:173]
	v_lshlrev_b32_e32 v172, 16, v184
	v_and_b32_e32 v173, 0xffff0000, v184
	v_pk_add_f32 v[162:163], v[162:163], v[174:175]
	s_waitcnt vmcnt(9)
	v_lshlrev_b32_e32 v174, 16, v199
	v_and_b32_e32 v175, 0xffff0000, v199
	v_pk_add_f32 v[166:167], v[166:167], v[172:173]
	v_lshlrev_b32_e32 v172, 16, v196
	v_and_b32_e32 v173, 0xffff0000, v196
	v_pk_add_f32 v[174:175], v[156:157], v[174:175]
	s_waitcnt vmcnt(8)
	v_lshlrev_b32_e32 v156, 16, v200
	v_and_b32_e32 v157, 0xffff0000, v200
	v_pk_add_f32 v[168:169], v[168:169], v[172:173]
	v_lshlrev_b32_e32 v172, 16, v198
	v_and_b32_e32 v173, 0xffff0000, v198
	v_pk_add_f32 v[164:165], v[164:165], v[156:157]
	s_waitcnt vmcnt(7)
	v_lshlrev_b32_e32 v156, 16, v202
	v_and_b32_e32 v157, 0xffff0000, v202
	v_pk_add_f32 v[170:171], v[170:171], v[172:173]
	v_lshlrev_b32_e32 v172, 16, v201
	v_and_b32_e32 v173, 0xffff0000, v201
	v_pk_add_f32 v[166:167], v[166:167], v[156:157]
	v_lshl_add_u32 v156, s2, 7, v215
	global_load_dwordx2 v[140:141], v[134:135], off sc1
	v_lshl_add_u64 v[132:133], v[132:133], 0, s[66:67]
	v_lshl_add_u64 v[130:131], v[130:131], 0, s[8:9]
	v_pk_add_f32 v[172:173], v[158:159], v[172:173]
	v_lshlrev_b32_e32 v158, 16, v203
	v_and_b32_e32 v159, 0xffff0000, v203
	s_lshl_b32 s33, s33, 4
	v_add_u32_e32 v157, s11, v156
	global_load_dwordx2 v[136:137], v[132:133], off sc1
	v_lshl_add_u64 v[132:133], v[130:131], 0, s[48:49]
	v_pk_add_f32 v[176:177], v[160:161], v[158:159]
	v_or_b32_e32 v158, s33, v157
	global_load_dwordx2 v[138:139], v[132:133], off sc1
	v_lshl_add_u64 v[132:133], v[130:131], 0, s[50:51]
	v_ashrrev_i32_e32 v159, 31, v158
	v_readlane_b32 s8, v254, 62
	global_load_dwordx2 v[134:135], v[132:133], off sc1
	v_lshl_add_u64 v[132:133], v[130:131], 0, s[46:47]
	v_lshl_or_b32 v160, s10, 8, v217
	v_lshlrev_b64 v[158:159], 11, v[158:159]
	v_readlane_b32 s9, v254, 63
	global_load_dwordx2 v[132:133], v[132:133], off sc1
	v_lshl_add_u64 v[130:131], v[130:131], 0, s[66:67]
	v_ashrrev_i32_e32 v161, 31, v160
	v_lshl_add_u64 v[158:159], s[8:9], 0, v[158:159]
	global_load_dwordx2 v[130:131], v[130:131], off sc1
	v_lshl_add_u64 v[178:179], v[160:161], 1, v[158:159]
	global_load_dwordx4 v[158:161], v[178:179], off
	s_waitcnt vmcnt(13)
	v_lshlrev_b32_e32 v180, 16, v152
	v_and_b32_e32 v181, 0xffff0000, v152
	v_lshlrev_b32_e32 v152, 16, v153
	v_and_b32_e32 v153, 0xffff0000, v153
	v_pk_add_f32 v[152:153], v[162:163], v[152:153]
	v_pk_add_f32 v[162:163], v[168:169], v[180:181]
	s_waitcnt vmcnt(12)
	v_lshlrev_b32_e32 v168, 16, v154
	v_and_b32_e32 v169, 0xffff0000, v154
	v_pk_add_f32 v[168:169], v[170:171], v[168:169]
	s_waitcnt vmcnt(11)
	v_lshlrev_b32_e32 v170, 16, v150
	v_and_b32_e32 v171, 0xffff0000, v150
	v_lshlrev_b32_e32 v150, 16, v151
	v_and_b32_e32 v151, 0xffff0000, v151
	v_pk_add_f32 v[164:165], v[164:165], v[170:171]
	v_pk_add_f32 v[170:171], v[172:173], v[150:151]
	s_waitcnt vmcnt(10)
	v_lshlrev_b32_e32 v150, 16, v148
	v_and_b32_e32 v151, 0xffff0000, v148
	v_lshlrev_b32_e32 v148, 16, v149
	v_and_b32_e32 v149, 0xffff0000, v149
	v_pk_add_f32 v[166:167], v[166:167], v[150:151]
	v_pk_add_f32 v[172:173], v[176:177], v[148:149]
	global_load_dwordx4 v[148:151], v[178:179], off offset:256
	v_lshlrev_b32_e32 v154, 16, v155
	v_and_b32_e32 v155, 0xffff0000, v155
	v_pk_add_f32 v[154:155], v[174:175], v[154:155]
	s_waitcnt vmcnt(10)
	v_lshlrev_b32_e32 v174, 16, v144
	v_and_b32_e32 v175, 0xffff0000, v144
	v_lshlrev_b32_e32 v144, 16, v145
	v_and_b32_e32 v145, 0xffff0000, v145
	v_pk_add_f32 v[144:145], v[152:153], v[144:145]
	s_waitcnt vmcnt(9)
	v_lshlrev_b32_e32 v152, 16, v146
	v_and_b32_e32 v153, 0xffff0000, v146
	v_lshlrev_b32_e32 v146, 16, v147
	v_and_b32_e32 v147, 0xffff0000, v147
	v_pk_add_f32 v[146:147], v[154:155], v[146:147]
	s_waitcnt vmcnt(8)
	v_lshlrev_b32_e32 v154, 16, v142
	v_and_b32_e32 v155, 0xffff0000, v142
	v_pk_add_f32 v[154:155], v[164:165], v[154:155]
	v_pk_add_f32 v[162:163], v[162:163], v[174:175]
	v_lshlrev_b32_e32 v142, 16, v143
	v_and_b32_e32 v143, 0xffff0000, v143
	v_pk_add_f32 v[142:143], v[170:171], v[142:143]
	v_pk_add_f32 v[152:153], v[168:169], v[152:153]
	s_waitcnt vmcnt(7)
	v_lshlrev_b32_e32 v164, 16, v140
	v_and_b32_e32 v165, 0xffff0000, v140
	v_pk_add_f32 v[164:165], v[166:167], v[164:165]
	v_lshlrev_b32_e32 v140, 16, v141
	v_and_b32_e32 v141, 0xffff0000, v141
	v_pk_add_f32 v[140:141], v[172:173], v[140:141]
	s_waitcnt vmcnt(6)
	v_lshlrev_b32_e32 v166, 16, v136
	v_and_b32_e32 v167, 0xffff0000, v136
	v_lshlrev_b32_e32 v136, 16, v137
	v_and_b32_e32 v137, 0xffff0000, v137
	v_pk_add_f32 v[136:137], v[144:145], v[136:137]
	v_pk_add_f32 v[144:145], v[162:163], v[166:167]
	s_waitcnt vmcnt(5)
	v_lshlrev_b32_e32 v162, 16, v138
	v_and_b32_e32 v163, 0xffff0000, v138
	v_lshlrev_b32_e32 v138, 16, v139
	v_and_b32_e32 v139, 0xffff0000, v139
	v_pk_add_f32 v[138:139], v[146:147], v[138:139]
	s_waitcnt vmcnt(4)
	v_lshlrev_b32_e32 v146, 16, v134
	v_and_b32_e32 v147, 0xffff0000, v134
	v_lshlrev_b32_e32 v134, 16, v135
	v_and_b32_e32 v135, 0xffff0000, v135
	v_pk_add_f32 v[134:135], v[142:143], v[134:135]
	s_waitcnt vmcnt(3)
	v_lshlrev_b32_e32 v142, 16, v132
	v_and_b32_e32 v143, 0xffff0000, v132
	v_lshlrev_b32_e32 v132, 16, v133
	v_and_b32_e32 v133, 0xffff0000, v133
	v_pk_add_f32 v[132:133], v[140:141], v[132:133]
	s_waitcnt vmcnt(2)
	v_lshlrev_b32_e32 v140, 16, v130
	v_and_b32_e32 v141, 0xffff0000, v130
	v_lshlrev_b32_e32 v130, 16, v131
	v_and_b32_e32 v131, 0xffff0000, v131
	v_pk_add_f32 v[152:153], v[152:153], v[162:163]
	v_pk_add_f32 v[140:141], v[144:145], v[140:141]
	v_pk_add_f32 v[136:137], v[136:137], v[130:131]
	s_waitcnt vmcnt(1)
	v_lshlrev_b32_e32 v130, 16, v158
	v_and_b32_e32 v131, 0xffff0000, v158
	v_lshlrev_b32_e32 v144, 16, v159
	v_and_b32_e32 v145, 0xffff0000, v159
	v_pk_add_f32 v[146:147], v[154:155], v[146:147]
	v_lshlrev_b32_e32 v154, 16, v160
	v_and_b32_e32 v155, 0xffff0000, v160
	v_pk_fma_f32 v[138:139], v[138:139], 0.5, v[144:145] op_sel_hi:[1,0,1]
	v_pk_fma_f32 v[130:131], v[152:153], 0.5, v[130:131] op_sel_hi:[1,0,1]
	v_lshlrev_b32_e32 v158, 16, v161
	v_and_b32_e32 v159, 0xffff0000, v161
	v_pk_fma_f32 v[144:145], v[146:147], 0.5, v[154:155] op_sel_hi:[1,0,1]
	v_mul_f32_e32 v146, v131, v131
	v_mul_f32_e32 v147, v139, v139
	v_pk_fma_f32 v[134:135], v[134:135], 0.5, v[158:159] op_sel_hi:[1,0,1]
	v_fmac_f32_e32 v146, v130, v130
	v_fmac_f32_e32 v147, v138, v138
	v_add_f32_e32 v146, v146, v147
	v_mul_f32_e32 v147, v145, v145
	v_mul_f32_e32 v152, v135, v135
	v_fmac_f32_e32 v147, v144, v144
	v_fmac_f32_e32 v152, v134, v134
	v_add_f32_e32 v147, v147, v152
	v_pk_add_f32 v[142:143], v[164:165], v[142:143]
	v_add_f32_e32 v152, v146, v147
	v_cvt_pk_bf16_f32 v130, v130, v131
	v_cvt_pk_bf16_f32 v131, v138, v139
	s_waitcnt vmcnt(0)
	v_lshlrev_b32_e32 v138, 16, v148
	v_and_b32_e32 v139, 0xffff0000, v148
	v_lshlrev_b32_e32 v146, 16, v149
	v_and_b32_e32 v147, 0xffff0000, v149
	v_pk_fma_f32 v[146:147], v[132:133], 0.5, v[146:147] op_sel_hi:[1,0,1]
	v_pk_fma_f32 v[138:139], v[142:143], 0.5, v[138:139] op_sel_hi:[1,0,1]
	v_lshlrev_b32_e32 v148, 16, v150
	v_and_b32_e32 v149, 0xffff0000, v150
	v_lshlrev_b32_e32 v150, 16, v151
	v_and_b32_e32 v151, 0xffff0000, v151
	v_mul_f32_e32 v132, v139, v139
	v_mul_f32_e32 v133, v147, v147
	v_pk_fma_f32 v[136:137], v[136:137], 0.5, v[150:151] op_sel_hi:[1,0,1]
	v_pk_fma_f32 v[140:141], v[140:141], 0.5, v[148:149] op_sel_hi:[1,0,1]
	v_fmac_f32_e32 v132, v138, v138
	v_fmac_f32_e32 v133, v146, v146
	v_add_f32_e32 v132, v132, v133
	v_mul_f32_e32 v133, v141, v141
	v_mul_f32_e32 v142, v137, v137
	v_fmac_f32_e32 v133, v140, v140
	v_fmac_f32_e32 v142, v136, v136
	v_add_f32_e32 v133, v133, v142
	v_add_f32_e32 v132, v132, v133
	v_and_b32_e32 v133, 64, v221
	v_add_f32_e32 v142, v152, v132
	v_xor_b32_e32 v132, 16, v221
	v_add_u32_e32 v143, 64, v133
	v_cmp_lt_i32_e32 vcc, v132, v143
	s_nop 1
	v_cndmask_b32_e32 v132, v221, v132, vcc
	v_lshlrev_b32_e32 v132, 2, v132
	v_mov_b32_e32 v148, v142
	s_nop 1
	v_permlane16_swap_b32_e32 v142, v148
	v_cvt_pk_bf16_f32 v132, v144, v145
	v_cvt_pk_bf16_f32 v133, v134, v135
	global_store_dwordx4 v[178:179], v[130:133], off
	s_nop 1
	v_xor_b32_e32 v131, 32, v221
	v_cmp_lt_i32_e32 vcc, v131, v143
	s_waitcnt lgkmcnt(0)
	v_add_f32_e32 v130, v142, v148
	v_cvt_pk_bf16_f32 v132, v138, v139
	v_cvt_pk_bf16_f32 v133, v146, v147
	v_cvt_pk_bf16_f32 v134, v140, v141
	v_cvt_pk_bf16_f32 v135, v136, v137
	v_cndmask_b32_e32 v131, v221, v131, vcc
	v_lshlrev_b32_e32 v131, 2, v131
	v_mov_b32_e32 v131, v130
	s_nop 1
	v_permlane32_swap_b32_e32 v130, v131
	global_store_dwordx4 v[178:179], v[132:135], off offset:256
	s_and_saveexec_b64 s[8:9], s[6:7]
	s_cbranch_execz .LBB0_411
	v_or_b32_e32 v132, s33, v156
	v_lshl_add_u32 v132, v132, 4, s42
	s_waitcnt lgkmcnt(0)
	v_add_f32_e32 v130, v130, v131
	ds_write_b32 v132, v130

.LBB0_412:
	s_lshl_b32 s2, s10, 8
	v_mov_b32_e32 v244, v213
	v_mov_b32_e32 v130, v1
	s_or_b32 s2, s2, s73
	s_lshl_b32 s11, s76, 8
	v_add_u32_e32 v229, s72, v130
	v_lshl_add_u32 v196, v244, 3, s2
	v_ashrrev_i32_e32 v197, 31, v196
	v_readlane_b32 s12, v254, 62
	v_add_u32_e32 v132, s11, v229
	v_lshlrev_b64 v[238:239], 1, v[196:197]
	v_readlane_b32 s13, v254, 63
	v_ashrrev_i32_e32 v133, 31, v132
	v_lshlrev_b64 v[240:241], 11, v[132:133]
	s_waitcnt lgkmcnt(0)
	v_lshl_add_u64 v[130:131], s[12:13], 0, v[238:239]
	v_lshl_add_u64 v[132:133], v[130:131], 0, v[240:241]
	global_load_dwordx4 v[230:233], v[132:133], off
	global_load_dwordx4 v[234:237], v[132:133], off offset:256
	v_add_u32_e32 v228, 16, v229
	v_add_u32_e32 v227, 32, v229
	v_add_u32_e32 v226, 48, v229
	v_add_u32_e32 v225, 0x80, v229
	v_add_u32_e32 v224, 0x90, v229
	v_add_u32_e32 v223, 0xa0, v229
	v_add_u32_e32 v222, 0xb0, v229
	v_add_u32_e32 v132, s11, v228
	v_add_u32_e32 v134, s11, v227
	v_add_u32_e32 v136, s11, v226
	v_add_u32_e32 v138, s11, v225
	v_add_u32_e32 v140, s11, v224
	v_add_u32_e32 v142, s11, v223
	v_add_u32_e32 v144, s11, v222
	v_ashrrev_i32_e32 v133, 31, v132
	v_ashrrev_i32_e32 v135, 31, v134
	v_ashrrev_i32_e32 v137, 31, v136
	v_ashrrev_i32_e32 v139, 31, v138
	v_ashrrev_i32_e32 v141, 31, v140
	v_ashrrev_i32_e32 v143, 31, v142
	v_ashrrev_i32_e32 v145, 31, v144
	v_lshlrev_b64 v[210:211], 11, v[132:133]
	v_lshlrev_b64 v[208:209], 11, v[134:135]
	v_lshlrev_b64 v[206:207], 11, v[136:137]
	v_lshlrev_b64 v[204:205], 11, v[138:139]
	v_lshlrev_b64 v[202:203], 11, v[140:141]
	v_lshlrev_b64 v[200:201], 11, v[142:143]
	v_lshlrev_b64 v[198:199], 11, v[144:145]
	v_lshl_add_u64 v[132:133], v[130:131], 0, v[210:211]
	v_lshl_add_u64 v[134:135], v[130:131], 0, v[208:209]
	v_lshl_add_u64 v[136:137], v[130:131], 0, v[206:207]
	v_lshl_add_u64 v[138:139], v[130:131], 0, v[204:205]
	v_lshl_add_u64 v[140:141], v[130:131], 0, v[202:203]
	v_lshl_add_u64 v[242:243], v[130:131], 0, v[200:201]
	v_lshl_add_u64 v[130:131], v[130:131], 0, v[198:199]
	global_load_dwordx4 v[182:185], v[132:133], off
	global_load_dwordx4 v[178:181], v[132:133], off offset:256
	global_load_dwordx4 v[174:177], v[134:135], off
	global_load_dwordx4 v[170:173], v[134:135], off offset:256
	global_load_dwordx4 v[166:169], v[136:137], off
	global_load_dwordx4 v[162:165], v[136:137], off offset:256
	global_load_dwordx4 v[158:161], v[138:139], off
	global_load_dwordx4 v[154:157], v[138:139], off offset:256
	global_load_dwordx4 v[150:153], v[140:141], off
	global_load_dwordx4 v[146:149], v[140:141], off offset:256
	global_load_dwordx4 v[142:145], v[242:243], off
	s_nop 0
	global_load_dwordx4 v[138:141], v[242:243], off offset:256
	global_load_dwordx4 v[134:137], v[130:131], off
	s_nop 0
	global_load_dwordx4 v[130:133], v[130:131], off offset:256
	v_cmp_eq_u32_e32 vcc, 0, v244
	s_waitcnt vmcnt(0)
	v_lshlrev_b32_e32 v242, 16, v230
	v_and_b32_e32 v243, 0xffff0000, v230
	v_lshlrev_b32_e32 v230, 16, v231
	v_and_b32_e32 v231, 0xffff0000, v231
	v_lshlrev_b32_e32 v244, 16, v232
	v_and_b32_e32 v245, 0xffff0000, v232
	v_lshlrev_b32_e32 v232, 16, v233
	v_and_b32_e32 v233, 0xffff0000, v233
	v_pk_fma_f32 v[128:129], v[128:129], 0.5, v[230:231] op_sel_hi:[1,0,1]
	v_pk_fma_f32 v[126:127], v[126:127], 0.5, v[242:243] op_sel_hi:[1,0,1]
	v_pk_fma_f32 v[230:231], v[124:125], 0.5, v[232:233] op_sel_hi:[1,0,1]
	v_pk_fma_f32 v[232:233], v[122:123], 0.5, v[244:245] op_sel_hi:[1,0,1]
	v_mul_f32_e32 v125, v127, v127
	v_mul_f32_e32 v242, v129, v129
	v_mul_f32_e32 v243, v233, v233
	v_mul_f32_e32 v244, v231, v231
	v_fmac_f32_e32 v125, v126, v126
	v_fmac_f32_e32 v242, v128, v128
	v_fmac_f32_e32 v243, v232, v232
	v_fmac_f32_e32 v244, v230, v230
	v_cvt_pk_bf16_f32 v122, v126, v127
	v_add_f32_e32 v125, v125, v242
	v_add_f32_e32 v126, v243, v244
	v_cvt_pk_bf16_f32 v123, v128, v129
	v_add_f32_e32 v242, v125, v126
	v_lshlrev_b32_e32 v126, 16, v234
	v_and_b32_e32 v127, 0xffff0000, v234
	v_lshlrev_b32_e32 v128, 16, v235
	v_and_b32_e32 v129, 0xffff0000, v235
	v_cvt_pk_bf16_f32 v124, v232, v233
	v_cvt_pk_bf16_f32 v125, v230, v231
	v_lshlrev_b32_e32 v230, 16, v236
	v_and_b32_e32 v231, 0xffff0000, v236
	v_pk_fma_f32 v[120:121], v[120:121], 0.5, v[128:129] op_sel_hi:[1,0,1]
	v_pk_fma_f32 v[118:119], v[118:119], 0.5, v[126:127] op_sel_hi:[1,0,1]
	v_lshlrev_b32_e32 v232, 16, v237
	v_and_b32_e32 v233, 0xffff0000, v237
	v_pk_fma_f32 v[128:129], v[114:115], 0.5, v[230:231] op_sel_hi:[1,0,1]
	v_mul_f32_e32 v114, v119, v119
	v_mul_f32_e32 v115, v121, v121
	v_pk_fma_f32 v[126:127], v[116:117], 0.5, v[232:233] op_sel_hi:[1,0,1]
	v_fmac_f32_e32 v114, v118, v118
	v_fmac_f32_e32 v115, v120, v120
	v_add_f32_e32 v114, v114, v115
	v_mul_f32_e32 v115, v129, v129
	v_mul_f32_e32 v116, v127, v127
	v_fmac_f32_e32 v115, v128, v128
	v_fmac_f32_e32 v116, v126, v126
	v_add_f32_e32 v115, v115, v116
	v_add_f32_e32 v114, v114, v115
	v_and_b32_e32 v116, 64, v221
	v_add_f32_e32 v115, v242, v114
	v_xor_b32_e32 v114, 16, v221
	v_add_u32_e32 v232, 64, v116
	v_cmp_lt_i32_e64 s[8:9], v114, v232
	v_lshl_add_u64 v[116:117], s[12:13], 0, v[240:241]
	v_lshl_add_u64 v[230:231], v[116:117], 0, v[238:239]
	v_cndmask_b32_e64 v114, v221, v114, s[8:9]
	v_lshlrev_b32_e32 v114, 2, v114
	v_mov_b32_e32 v233, v115
	s_nop 1
	v_permlane16_swap_b32_e32 v115, v233
	global_store_dwordx4 v[230:231], v[122:125], off
	v_cvt_pk_bf16_f32 v118, v118, v119
	v_cvt_pk_bf16_f32 v119, v120, v121
	v_cvt_pk_bf16_f32 v120, v128, v129
	s_waitcnt lgkmcnt(0)
	v_add_f32_e32 v116, v115, v233
	v_xor_b32_e32 v115, 32, v221
	v_cmp_lt_i32_e64 s[8:9], v115, v232
	v_cvt_pk_bf16_f32 v121, v126, v127
	global_store_dwordx4 v[230:231], v[118:121], off offset:256
	s_nop 0
	v_cndmask_b32_e64 v115, v221, v115, s[8:9]
	v_lshlrev_b32_e32 v115, 2, v115
	v_mov_b32_e32 v117, v116
	s_nop 1
	v_permlane32_swap_b32_e32 v116, v117
	s_and_saveexec_b64 s[8:9], vcc
	s_cbranch_execz .LBB0_414
	s_waitcnt lgkmcnt(0)
	v_add_f32_e32 v116, v116, v117
	v_lshl_add_u32 v117, v229, 4, s42
	ds_write_b32 v117, v116
.LBB0_414:
	s_or_b64 exec, exec, s[8:9]
	v_lshlrev_b32_e32 v116, 16, v182
	s_waitcnt lgkmcnt(0)
	v_and_b32_e32 v117, 0xffff0000, v182
	v_lshlrev_b32_e32 v118, 16, v183
	v_and_b32_e32 v119, 0xffff0000, v183
	v_lshlrev_b32_e32 v120, 16, v184
	v_and_b32_e32 v121, 0xffff0000, v184
	v_lshlrev_b32_e32 v122, 16, v185
	v_and_b32_e32 v123, 0xffff0000, v185
	v_pk_fma_f32 v[112:113], v[112:113], 0.5, v[118:119] op_sel_hi:[1,0,1]
	v_pk_fma_f32 v[110:111], v[110:111], 0.5, v[116:117] op_sel_hi:[1,0,1]
	v_pk_fma_f32 v[116:117], v[108:109], 0.5, v[122:123] op_sel_hi:[1,0,1]
	v_pk_fma_f32 v[108:109], v[106:107], 0.5, v[120:121] op_sel_hi:[1,0,1]
	v_mul_f32_e32 v106, v111, v111
	v_mul_f32_e32 v107, v113, v113
	v_fmac_f32_e32 v106, v110, v110
	v_fmac_f32_e32 v107, v112, v112
	v_add_f32_e32 v106, v106, v107
	v_mul_f32_e32 v107, v109, v109
	v_mul_f32_e32 v118, v117, v117
	v_fmac_f32_e32 v107, v108, v108
	v_fmac_f32_e32 v118, v116, v116
	v_add_f32_e32 v107, v107, v118
	v_add_f32_e32 v120, v106, v107
	v_cvt_pk_bf16_f32 v106, v110, v111
	v_cvt_pk_bf16_f32 v107, v112, v113
	v_lshlrev_b32_e32 v110, 16, v178
	v_and_b32_e32 v111, 0xffff0000, v178
	v_lshlrev_b32_e32 v112, 16, v179
	v_and_b32_e32 v113, 0xffff0000, v179
	v_cvt_pk_bf16_f32 v108, v108, v109
	v_cvt_pk_bf16_f32 v109, v116, v117
	v_lshlrev_b32_e32 v116, 16, v180
	v_and_b32_e32 v117, 0xffff0000, v180
	v_pk_fma_f32 v[104:105], v[104:105], 0.5, v[112:113] op_sel_hi:[1,0,1]
	v_pk_fma_f32 v[102:103], v[102:103], 0.5, v[110:111] op_sel_hi:[1,0,1]
	v_lshlrev_b32_e32 v118, 16, v181
	v_and_b32_e32 v119, 0xffff0000, v181
	v_pk_fma_f32 v[112:113], v[98:99], 0.5, v[116:117] op_sel_hi:[1,0,1]
	v_mul_f32_e32 v98, v103, v103
	v_mul_f32_e32 v99, v105, v105
	v_pk_fma_f32 v[110:111], v[100:101], 0.5, v[118:119] op_sel_hi:[1,0,1]
	v_fmac_f32_e32 v98, v102, v102
	v_fmac_f32_e32 v99, v104, v104
	v_add_f32_e32 v98, v98, v99
	v_mul_f32_e32 v99, v113, v113
	v_mul_f32_e32 v100, v111, v111
	v_fmac_f32_e32 v99, v112, v112
	v_fmac_f32_e32 v100, v110, v110
	v_add_f32_e32 v99, v99, v100
	v_add_f32_e32 v98, v98, v99
	v_add_f32_e32 v101, v120, v98
	v_mov_b32_e32 v118, v101
	s_nop 1
	v_permlane16_swap_b32_e32 v101, v118
	v_readlane_b32 s8, v254, 62
	v_readlane_b32 s9, v254, 63
	s_nop 1
	v_lshl_add_u64 v[98:99], s[8:9], 0, v[210:211]
	v_lshl_add_u64 v[116:117], v[196:197], 1, v[98:99]
	s_waitcnt lgkmcnt(0)
	v_add_f32_e32 v98, v101, v118
	v_mov_b32_e32 v99, v98
	s_nop 1
	v_permlane32_swap_b32_e32 v98, v99
	global_store_dwordx4 v[116:117], v[106:109], off
	v_cvt_pk_bf16_f32 v100, v102, v103
	v_cvt_pk_bf16_f32 v101, v104, v105
	v_cvt_pk_bf16_f32 v102, v112, v113
	v_cvt_pk_bf16_f32 v103, v110, v111
	global_store_dwordx4 v[116:117], v[100:103], off offset:256
	s_and_saveexec_b64 s[8:9], vcc
	s_cbranch_execz .LBB0_416
	s_waitcnt lgkmcnt(0)
	v_add_f32_e32 v98, v98, v99
	v_lshl_add_u32 v99, v228, 4, s42
	ds_write_b32 v99, v98
.LBB0_416:
	s_or_b64 exec, exec, s[8:9]
	v_lshlrev_b32_e32 v98, 16, v174
	s_waitcnt lgkmcnt(0)
	v_and_b32_e32 v99, 0xffff0000, v174
	v_lshlrev_b32_e32 v100, 16, v175
	v_and_b32_e32 v101, 0xffff0000, v175
	v_lshlrev_b32_e32 v102, 16, v176
	v_and_b32_e32 v103, 0xffff0000, v176
	v_lshlrev_b32_e32 v104, 16, v177
	v_and_b32_e32 v105, 0xffff0000, v177
	v_pk_fma_f32 v[96:97], v[96:97], 0.5, v[100:101] op_sel_hi:[1,0,1]
	v_pk_fma_f32 v[94:95], v[94:95], 0.5, v[98:99] op_sel_hi:[1,0,1]
	v_pk_fma_f32 v[98:99], v[92:93], 0.5, v[104:105] op_sel_hi:[1,0,1]
	v_pk_fma_f32 v[92:93], v[90:91], 0.5, v[102:103] op_sel_hi:[1,0,1]
	v_mul_f32_e32 v90, v95, v95
	v_mul_f32_e32 v91, v97, v97
	v_fmac_f32_e32 v90, v94, v94
	v_fmac_f32_e32 v91, v96, v96
	v_add_f32_e32 v90, v90, v91
	v_mul_f32_e32 v91, v93, v93
	v_mul_f32_e32 v100, v99, v99
	v_fmac_f32_e32 v91, v92, v92
	v_fmac_f32_e32 v100, v98, v98
	v_add_f32_e32 v91, v91, v100
	v_add_f32_e32 v102, v90, v91
	v_cvt_pk_bf16_f32 v90, v94, v95
	v_cvt_pk_bf16_f32 v91, v96, v97
	v_lshlrev_b32_e32 v94, 16, v170
	v_and_b32_e32 v95, 0xffff0000, v170
	v_lshlrev_b32_e32 v96, 16, v171
	v_and_b32_e32 v97, 0xffff0000, v171
	v_cvt_pk_bf16_f32 v92, v92, v93
	v_cvt_pk_bf16_f32 v93, v98, v99
	v_lshlrev_b32_e32 v98, 16, v172
	v_and_b32_e32 v99, 0xffff0000, v172
	v_pk_fma_f32 v[88:89], v[88:89], 0.5, v[96:97] op_sel_hi:[1,0,1]
	v_pk_fma_f32 v[86:87], v[86:87], 0.5, v[94:95] op_sel_hi:[1,0,1]
	v_lshlrev_b32_e32 v100, 16, v173
	v_and_b32_e32 v101, 0xffff0000, v173
	v_pk_fma_f32 v[96:97], v[82:83], 0.5, v[98:99] op_sel_hi:[1,0,1]
	v_mul_f32_e32 v82, v87, v87
	v_mul_f32_e32 v83, v89, v89
	v_pk_fma_f32 v[94:95], v[84:85], 0.5, v[100:101] op_sel_hi:[1,0,1]
	v_fmac_f32_e32 v82, v86, v86
	v_fmac_f32_e32 v83, v88, v88
	v_add_f32_e32 v82, v82, v83
	v_mul_f32_e32 v83, v97, v97
	v_mul_f32_e32 v84, v95, v95
	v_fmac_f32_e32 v83, v96, v96
	v_fmac_f32_e32 v84, v94, v94
	v_add_f32_e32 v83, v83, v84
	v_add_f32_e32 v82, v82, v83
	v_add_f32_e32 v85, v102, v82
	v_mov_b32_e32 v100, v85
	s_nop 1
	v_permlane16_swap_b32_e32 v85, v100
	v_readlane_b32 s8, v254, 62
	v_readlane_b32 s9, v254, 63
	s_nop 1
	v_lshl_add_u64 v[82:83], s[8:9], 0, v[208:209]
	v_lshl_add_u64 v[98:99], v[196:197], 1, v[82:83]
	s_waitcnt lgkmcnt(0)
	v_add_f32_e32 v82, v85, v100
	v_mov_b32_e32 v83, v82
	s_nop 1
	v_permlane32_swap_b32_e32 v82, v83
	global_store_dwordx4 v[98:99], v[90:93], off
	v_cvt_pk_bf16_f32 v84, v86, v87
	v_cvt_pk_bf16_f32 v85, v88, v89
	v_cvt_pk_bf16_f32 v86, v96, v97
	v_cvt_pk_bf16_f32 v87, v94, v95
	global_store_dwordx4 v[98:99], v[84:87], off offset:256
	s_and_saveexec_b64 s[8:9], vcc
	s_cbranch_execz .LBB0_418
	s_waitcnt lgkmcnt(0)
	v_add_f32_e32 v82, v82, v83
	v_lshl_add_u32 v83, v227, 4, s42
	ds_write_b32 v83, v82
.LBB0_418:
	s_or_b64 exec, exec, s[8:9]
	v_lshlrev_b32_e32 v82, 16, v166
	s_waitcnt lgkmcnt(0)
	v_and_b32_e32 v83, 0xffff0000, v166
	v_lshlrev_b32_e32 v84, 16, v167
	v_and_b32_e32 v85, 0xffff0000, v167
	v_lshlrev_b32_e32 v86, 16, v168
	v_and_b32_e32 v87, 0xffff0000, v168
	v_lshlrev_b32_e32 v88, 16, v169
	v_and_b32_e32 v89, 0xffff0000, v169
	v_pk_fma_f32 v[80:81], v[80:81], 0.5, v[84:85] op_sel_hi:[1,0,1]
	v_pk_fma_f32 v[78:79], v[78:79], 0.5, v[82:83] op_sel_hi:[1,0,1]
	v_pk_fma_f32 v[82:83], v[76:77], 0.5, v[88:89] op_sel_hi:[1,0,1]
	v_pk_fma_f32 v[76:77], v[74:75], 0.5, v[86:87] op_sel_hi:[1,0,1]
	v_mul_f32_e32 v74, v79, v79
	v_mul_f32_e32 v75, v81, v81
	v_fmac_f32_e32 v74, v78, v78
	v_fmac_f32_e32 v75, v80, v80
	v_add_f32_e32 v74, v74, v75
	v_mul_f32_e32 v75, v77, v77
	v_mul_f32_e32 v84, v83, v83
	v_fmac_f32_e32 v75, v76, v76
	v_fmac_f32_e32 v84, v82, v82
	v_add_f32_e32 v75, v75, v84
	v_add_f32_e32 v86, v74, v75
	v_cvt_pk_bf16_f32 v74, v78, v79
	v_cvt_pk_bf16_f32 v75, v80, v81
	v_lshlrev_b32_e32 v78, 16, v162
	v_and_b32_e32 v79, 0xffff0000, v162
	v_lshlrev_b32_e32 v80, 16, v163
	v_and_b32_e32 v81, 0xffff0000, v163
	v_cvt_pk_bf16_f32 v76, v76, v77
	v_cvt_pk_bf16_f32 v77, v82, v83
	v_lshlrev_b32_e32 v82, 16, v164
	v_and_b32_e32 v83, 0xffff0000, v164
	v_pk_fma_f32 v[72:73], v[72:73], 0.5, v[80:81] op_sel_hi:[1,0,1]
	v_pk_fma_f32 v[70:71], v[70:71], 0.5, v[78:79] op_sel_hi:[1,0,1]
	v_lshlrev_b32_e32 v84, 16, v165
	v_and_b32_e32 v85, 0xffff0000, v165
	v_pk_fma_f32 v[80:81], v[66:67], 0.5, v[82:83] op_sel_hi:[1,0,1]
	v_mul_f32_e32 v66, v71, v71
	v_mul_f32_e32 v67, v73, v73
	v_pk_fma_f32 v[78:79], v[68:69], 0.5, v[84:85] op_sel_hi:[1,0,1]
	v_fmac_f32_e32 v66, v70, v70
	v_fmac_f32_e32 v67, v72, v72
	v_add_f32_e32 v66, v66, v67
	v_mul_f32_e32 v67, v81, v81
	v_mul_f32_e32 v68, v79, v79
	v_fmac_f32_e32 v67, v80, v80
	v_fmac_f32_e32 v68, v78, v78
	v_add_f32_e32 v67, v67, v68
	v_add_f32_e32 v66, v66, v67
	v_add_f32_e32 v69, v86, v66
	v_mov_b32_e32 v84, v69
	s_nop 1
	v_permlane16_swap_b32_e32 v69, v84
	v_readlane_b32 s8, v254, 62
	v_readlane_b32 s9, v254, 63
	s_nop 1
	v_lshl_add_u64 v[66:67], s[8:9], 0, v[206:207]
	v_lshl_add_u64 v[82:83], v[196:197], 1, v[66:67]
	s_waitcnt lgkmcnt(0)
	v_add_f32_e32 v66, v69, v84
	v_mov_b32_e32 v67, v66
	s_nop 1
	v_permlane32_swap_b32_e32 v66, v67
	global_store_dwordx4 v[82:83], v[74:77], off
	v_cvt_pk_bf16_f32 v68, v70, v71
	v_cvt_pk_bf16_f32 v69, v72, v73
	v_cvt_pk_bf16_f32 v70, v80, v81
	v_cvt_pk_bf16_f32 v71, v78, v79
	global_store_dwordx4 v[82:83], v[68:71], off offset:256
	s_and_saveexec_b64 s[8:9], vcc
	s_cbranch_execz .LBB0_420
	s_waitcnt lgkmcnt(0)
	v_add_f32_e32 v66, v66, v67
	v_lshl_add_u32 v67, v226, 4, s42
	ds_write_b32 v67, v66
.LBB0_420:
	s_or_b64 exec, exec, s[8:9]
	v_lshlrev_b32_e32 v66, 16, v158
	s_waitcnt lgkmcnt(0)
	v_and_b32_e32 v67, 0xffff0000, v158
	v_lshlrev_b32_e32 v68, 16, v159
	v_and_b32_e32 v69, 0xffff0000, v159
	v_lshlrev_b32_e32 v70, 16, v160
	v_and_b32_e32 v71, 0xffff0000, v160
	v_lshlrev_b32_e32 v72, 16, v161
	v_and_b32_e32 v73, 0xffff0000, v161
	v_pk_fma_f32 v[64:65], v[64:65], 0.5, v[68:69] op_sel_hi:[1,0,1]
	v_pk_fma_f32 v[62:63], v[62:63], 0.5, v[66:67] op_sel_hi:[1,0,1]
	v_pk_fma_f32 v[66:67], v[60:61], 0.5, v[72:73] op_sel_hi:[1,0,1]
	v_pk_fma_f32 v[60:61], v[58:59], 0.5, v[70:71] op_sel_hi:[1,0,1]
	v_mul_f32_e32 v58, v63, v63
	v_mul_f32_e32 v59, v65, v65
	v_fmac_f32_e32 v58, v62, v62
	v_fmac_f32_e32 v59, v64, v64
	v_add_f32_e32 v58, v58, v59
	v_mul_f32_e32 v59, v61, v61
	v_mul_f32_e32 v68, v67, v67
	v_fmac_f32_e32 v59, v60, v60
	v_fmac_f32_e32 v68, v66, v66
	v_add_f32_e32 v59, v59, v68
	v_add_f32_e32 v70, v58, v59
	v_cvt_pk_bf16_f32 v58, v62, v63
	v_cvt_pk_bf16_f32 v59, v64, v65
	v_lshlrev_b32_e32 v62, 16, v154
	v_and_b32_e32 v63, 0xffff0000, v154
	v_lshlrev_b32_e32 v64, 16, v155
	v_and_b32_e32 v65, 0xffff0000, v155
	v_cvt_pk_bf16_f32 v60, v60, v61
	v_cvt_pk_bf16_f32 v61, v66, v67
	v_lshlrev_b32_e32 v66, 16, v156
	v_and_b32_e32 v67, 0xffff0000, v156
	v_pk_fma_f32 v[56:57], v[56:57], 0.5, v[64:65] op_sel_hi:[1,0,1]
	v_pk_fma_f32 v[54:55], v[54:55], 0.5, v[62:63] op_sel_hi:[1,0,1]
	v_lshlrev_b32_e32 v68, 16, v157
	v_and_b32_e32 v69, 0xffff0000, v157
	v_pk_fma_f32 v[64:65], v[50:51], 0.5, v[66:67] op_sel_hi:[1,0,1]
	v_mul_f32_e32 v50, v55, v55
	v_mul_f32_e32 v51, v57, v57
	v_pk_fma_f32 v[62:63], v[52:53], 0.5, v[68:69] op_sel_hi:[1,0,1]
	v_fmac_f32_e32 v50, v54, v54
	v_fmac_f32_e32 v51, v56, v56
	v_add_f32_e32 v50, v50, v51
	v_mul_f32_e32 v51, v65, v65
	v_mul_f32_e32 v52, v63, v63
	v_fmac_f32_e32 v51, v64, v64
	v_fmac_f32_e32 v52, v62, v62
	v_add_f32_e32 v51, v51, v52
	v_add_f32_e32 v50, v50, v51
	v_add_f32_e32 v53, v70, v50
	v_mov_b32_e32 v68, v53
	s_nop 1
	v_permlane16_swap_b32_e32 v53, v68
	v_readlane_b32 s8, v254, 62
	v_readlane_b32 s9, v254, 63
	s_nop 1
	v_lshl_add_u64 v[50:51], s[8:9], 0, v[204:205]
	v_lshl_add_u64 v[66:67], v[196:197], 1, v[50:51]
	s_waitcnt lgkmcnt(0)
	v_add_f32_e32 v50, v53, v68
	v_mov_b32_e32 v51, v50
	s_nop 1
	v_permlane32_swap_b32_e32 v50, v51
	global_store_dwordx4 v[66:67], v[58:61], off
	v_cvt_pk_bf16_f32 v52, v54, v55
	v_cvt_pk_bf16_f32 v53, v56, v57
	v_cvt_pk_bf16_f32 v54, v64, v65
	v_cvt_pk_bf16_f32 v55, v62, v63
	global_store_dwordx4 v[66:67], v[52:55], off offset:256
	s_and_saveexec_b64 s[8:9], vcc
	s_cbranch_execz .LBB0_422
	s_waitcnt lgkmcnt(0)
	v_add_f32_e32 v50, v50, v51
	v_lshl_add_u32 v51, v225, 4, s42
	ds_write_b32 v51, v50
.LBB0_422:
	s_or_b64 exec, exec, s[8:9]
	v_lshlrev_b32_e32 v50, 16, v150
	s_waitcnt lgkmcnt(0)
	v_and_b32_e32 v51, 0xffff0000, v150
	v_lshlrev_b32_e32 v52, 16, v151
	v_and_b32_e32 v53, 0xffff0000, v151
	v_lshlrev_b32_e32 v54, 16, v152
	v_and_b32_e32 v55, 0xffff0000, v152
	v_lshlrev_b32_e32 v56, 16, v153
	v_and_b32_e32 v57, 0xffff0000, v153
	v_pk_fma_f32 v[48:49], v[48:49], 0.5, v[52:53] op_sel_hi:[1,0,1]
	v_pk_fma_f32 v[46:47], v[46:47], 0.5, v[50:51] op_sel_hi:[1,0,1]
	v_pk_fma_f32 v[50:51], v[44:45], 0.5, v[56:57] op_sel_hi:[1,0,1]
	v_pk_fma_f32 v[44:45], v[42:43], 0.5, v[54:55] op_sel_hi:[1,0,1]
	v_mul_f32_e32 v42, v47, v47
	v_mul_f32_e32 v43, v49, v49
	v_fmac_f32_e32 v42, v46, v46
	v_fmac_f32_e32 v43, v48, v48
	v_add_f32_e32 v42, v42, v43
	v_mul_f32_e32 v43, v45, v45
	v_mul_f32_e32 v52, v51, v51
	v_fmac_f32_e32 v43, v44, v44
	v_fmac_f32_e32 v52, v50, v50
	v_add_f32_e32 v43, v43, v52
	v_add_f32_e32 v54, v42, v43
	v_cvt_pk_bf16_f32 v42, v46, v47
	v_cvt_pk_bf16_f32 v43, v48, v49
	v_lshlrev_b32_e32 v46, 16, v146
	v_and_b32_e32 v47, 0xffff0000, v146
	v_lshlrev_b32_e32 v48, 16, v147
	v_and_b32_e32 v49, 0xffff0000, v147
	v_cvt_pk_bf16_f32 v44, v44, v45
	v_cvt_pk_bf16_f32 v45, v50, v51
	v_lshlrev_b32_e32 v50, 16, v148
	v_and_b32_e32 v51, 0xffff0000, v148
	v_pk_fma_f32 v[40:41], v[40:41], 0.5, v[48:49] op_sel_hi:[1,0,1]
	v_pk_fma_f32 v[38:39], v[38:39], 0.5, v[46:47] op_sel_hi:[1,0,1]
	v_lshlrev_b32_e32 v52, 16, v149
	v_and_b32_e32 v53, 0xffff0000, v149
	v_pk_fma_f32 v[48:49], v[34:35], 0.5, v[50:51] op_sel_hi:[1,0,1]
	v_mul_f32_e32 v34, v39, v39
	v_mul_f32_e32 v35, v41, v41
	v_pk_fma_f32 v[46:47], v[36:37], 0.5, v[52:53] op_sel_hi:[1,0,1]
	v_fmac_f32_e32 v34, v38, v38
	v_fmac_f32_e32 v35, v40, v40
	v_add_f32_e32 v34, v34, v35
	v_mul_f32_e32 v35, v49, v49
	v_mul_f32_e32 v36, v47, v47
	v_fmac_f32_e32 v35, v48, v48
	v_fmac_f32_e32 v36, v46, v46
	v_add_f32_e32 v35, v35, v36
	v_add_f32_e32 v34, v34, v35
	v_add_f32_e32 v37, v54, v34
	v_mov_b32_e32 v52, v37
	s_nop 1
	v_permlane16_swap_b32_e32 v37, v52
	v_readlane_b32 s8, v254, 62
	v_readlane_b32 s9, v254, 63
	s_nop 1
	v_lshl_add_u64 v[34:35], s[8:9], 0, v[202:203]
	v_lshl_add_u64 v[50:51], v[196:197], 1, v[34:35]
	s_waitcnt lgkmcnt(0)
	v_add_f32_e32 v34, v37, v52
	v_mov_b32_e32 v35, v34
	s_nop 1
	v_permlane32_swap_b32_e32 v34, v35
	global_store_dwordx4 v[50:51], v[42:45], off
	v_cvt_pk_bf16_f32 v36, v38, v39
	v_cvt_pk_bf16_f32 v37, v40, v41
	v_cvt_pk_bf16_f32 v38, v48, v49
	v_cvt_pk_bf16_f32 v39, v46, v47
	global_store_dwordx4 v[50:51], v[36:39], off offset:256
	s_and_saveexec_b64 s[8:9], vcc
	s_cbranch_execz .LBB0_424
	s_waitcnt lgkmcnt(0)
	v_add_f32_e32 v34, v34, v35
	v_lshl_add_u32 v35, v224, 4, s42
	ds_write_b32 v35, v34
.LBB0_424:
	s_or_b64 exec, exec, s[8:9]
	v_lshlrev_b32_e32 v34, 16, v142
	s_waitcnt lgkmcnt(0)
	v_and_b32_e32 v35, 0xffff0000, v142
	v_lshlrev_b32_e32 v36, 16, v143
	v_and_b32_e32 v37, 0xffff0000, v143
	v_lshlrev_b32_e32 v38, 16, v144
	v_and_b32_e32 v39, 0xffff0000, v144
	v_lshlrev_b32_e32 v40, 16, v145
	v_and_b32_e32 v41, 0xffff0000, v145
	v_pk_fma_f32 v[32:33], v[32:33], 0.5, v[36:37] op_sel_hi:[1,0,1]
	v_pk_fma_f32 v[30:31], v[30:31], 0.5, v[34:35] op_sel_hi:[1,0,1]
	v_pk_fma_f32 v[34:35], v[28:29], 0.5, v[40:41] op_sel_hi:[1,0,1]
	v_pk_fma_f32 v[28:29], v[26:27], 0.5, v[38:39] op_sel_hi:[1,0,1]
	v_mul_f32_e32 v26, v31, v31
	v_mul_f32_e32 v27, v33, v33
	v_fmac_f32_e32 v26, v30, v30
	v_fmac_f32_e32 v27, v32, v32
	v_add_f32_e32 v26, v26, v27
	v_mul_f32_e32 v27, v29, v29
	v_mul_f32_e32 v36, v35, v35
	v_fmac_f32_e32 v27, v28, v28
	v_fmac_f32_e32 v36, v34, v34
	v_add_f32_e32 v27, v27, v36
	v_add_f32_e32 v38, v26, v27
	v_cvt_pk_bf16_f32 v26, v30, v31
	v_cvt_pk_bf16_f32 v27, v32, v33
	v_lshlrev_b32_e32 v30, 16, v138
	v_and_b32_e32 v31, 0xffff0000, v138
	v_lshlrev_b32_e32 v32, 16, v139
	v_and_b32_e32 v33, 0xffff0000, v139
	v_cvt_pk_bf16_f32 v28, v28, v29
	v_cvt_pk_bf16_f32 v29, v34, v35
	v_lshlrev_b32_e32 v34, 16, v140
	v_and_b32_e32 v35, 0xffff0000, v140
	v_pk_fma_f32 v[24:25], v[24:25], 0.5, v[32:33] op_sel_hi:[1,0,1]
	v_pk_fma_f32 v[22:23], v[22:23], 0.5, v[30:31] op_sel_hi:[1,0,1]
	v_lshlrev_b32_e32 v36, 16, v141
	v_and_b32_e32 v37, 0xffff0000, v141
	v_pk_fma_f32 v[32:33], v[18:19], 0.5, v[34:35] op_sel_hi:[1,0,1]
	v_mul_f32_e32 v18, v23, v23
	v_mul_f32_e32 v19, v25, v25
	v_pk_fma_f32 v[30:31], v[20:21], 0.5, v[36:37] op_sel_hi:[1,0,1]
	v_fmac_f32_e32 v18, v22, v22
	v_fmac_f32_e32 v19, v24, v24
	v_add_f32_e32 v18, v18, v19
	v_mul_f32_e32 v19, v33, v33
	v_mul_f32_e32 v20, v31, v31
	v_fmac_f32_e32 v19, v32, v32
	v_fmac_f32_e32 v20, v30, v30
	v_add_f32_e32 v19, v19, v20
	v_add_f32_e32 v18, v18, v19
	v_add_f32_e32 v21, v38, v18
	v_mov_b32_e32 v36, v21
	s_nop 1
	v_permlane16_swap_b32_e32 v21, v36
	v_readlane_b32 s8, v254, 62
	v_readlane_b32 s9, v254, 63
	s_nop 1
	v_lshl_add_u64 v[18:19], s[8:9], 0, v[200:201]
	v_lshl_add_u64 v[34:35], v[196:197], 1, v[18:19]
	s_waitcnt lgkmcnt(0)
	v_add_f32_e32 v18, v21, v36
	v_mov_b32_e32 v19, v18
	s_nop 1
	v_permlane32_swap_b32_e32 v18, v19
	global_store_dwordx4 v[34:35], v[26:29], off
	v_cvt_pk_bf16_f32 v20, v22, v23
	v_cvt_pk_bf16_f32 v21, v24, v25
	v_cvt_pk_bf16_f32 v22, v32, v33
	v_cvt_pk_bf16_f32 v23, v30, v31
	global_store_dwordx4 v[34:35], v[20:23], off offset:256
	s_and_saveexec_b64 s[8:9], vcc
	s_cbranch_execz .LBB0_426
	s_waitcnt lgkmcnt(0)
	v_add_f32_e32 v18, v18, v19
	v_lshl_add_u32 v19, v223, 4, s42
	ds_write_b32 v19, v18
.LBB0_426:
	s_or_b64 exec, exec, s[8:9]
	v_lshlrev_b32_e32 v18, 16, v134
	s_waitcnt lgkmcnt(0)
	v_and_b32_e32 v19, 0xffff0000, v134
	v_lshlrev_b32_e32 v20, 16, v135
	v_and_b32_e32 v21, 0xffff0000, v135
	v_lshlrev_b32_e32 v22, 16, v136
	v_and_b32_e32 v23, 0xffff0000, v136
	v_lshlrev_b32_e32 v24, 16, v137
	v_and_b32_e32 v25, 0xffff0000, v137
	v_pk_fma_f32 v[16:17], v[16:17], 0.5, v[20:21] op_sel_hi:[1,0,1]
	v_pk_fma_f32 v[14:15], v[14:15], 0.5, v[18:19] op_sel_hi:[1,0,1]
	v_pk_fma_f32 v[18:19], v[12:13], 0.5, v[24:25] op_sel_hi:[1,0,1]
	v_pk_fma_f32 v[12:13], v[10:11], 0.5, v[22:23] op_sel_hi:[1,0,1]
	v_mul_f32_e32 v10, v15, v15
	v_mul_f32_e32 v11, v17, v17
	v_fmac_f32_e32 v10, v14, v14
	v_fmac_f32_e32 v11, v16, v16
	v_add_f32_e32 v10, v10, v11
	v_mul_f32_e32 v11, v13, v13
	v_mul_f32_e32 v20, v19, v19
	v_fmac_f32_e32 v11, v12, v12
	v_fmac_f32_e32 v20, v18, v18
	v_add_f32_e32 v11, v11, v20
	v_add_f32_e32 v22, v10, v11
	v_cvt_pk_bf16_f32 v10, v14, v15
	v_cvt_pk_bf16_f32 v11, v16, v17
	v_lshlrev_b32_e32 v14, 16, v130
	v_and_b32_e32 v15, 0xffff0000, v130
	v_lshlrev_b32_e32 v16, 16, v131
	v_and_b32_e32 v17, 0xffff0000, v131
	v_cvt_pk_bf16_f32 v12, v12, v13
	v_cvt_pk_bf16_f32 v13, v18, v19
	v_lshlrev_b32_e32 v18, 16, v132
	v_and_b32_e32 v19, 0xffff0000, v132
	v_pk_fma_f32 v[8:9], v[8:9], 0.5, v[16:17] op_sel_hi:[1,0,1]
	v_pk_fma_f32 v[6:7], v[6:7], 0.5, v[14:15] op_sel_hi:[1,0,1]
	v_lshlrev_b32_e32 v20, 16, v133
	v_and_b32_e32 v21, 0xffff0000, v133
	v_pk_fma_f32 v[16:17], v[2:3], 0.5, v[18:19] op_sel_hi:[1,0,1]
	v_mul_f32_e32 v2, v7, v7
	v_mul_f32_e32 v3, v9, v9
	v_pk_fma_f32 v[14:15], v[4:5], 0.5, v[20:21] op_sel_hi:[1,0,1]
	v_fmac_f32_e32 v2, v6, v6
	v_fmac_f32_e32 v3, v8, v8
	v_add_f32_e32 v2, v2, v3
	v_mul_f32_e32 v3, v17, v17
	v_mul_f32_e32 v4, v15, v15
	v_fmac_f32_e32 v3, v16, v16
	v_fmac_f32_e32 v4, v14, v14
	v_add_f32_e32 v3, v3, v4
	v_add_f32_e32 v2, v2, v3
	v_add_f32_e32 v5, v22, v2
	v_mov_b32_e32 v20, v5
	s_nop 1
	v_permlane16_swap_b32_e32 v5, v20
	v_readlane_b32 s8, v254, 62
	v_readlane_b32 s9, v254, 63
	s_nop 1
	v_lshl_add_u64 v[2:3], s[8:9], 0, v[198:199]
	v_lshl_add_u64 v[18:19], v[196:197], 1, v[2:3]
	s_waitcnt lgkmcnt(0)
	v_add_f32_e32 v2, v5, v20
	v_mov_b32_e32 v3, v2
	s_nop 1
	v_permlane32_swap_b32_e32 v2, v3
	global_store_dwordx4 v[18:19], v[10:13], off
	v_cvt_pk_bf16_f32 v4, v6, v7
	v_cvt_pk_bf16_f32 v5, v8, v9
	v_cvt_pk_bf16_f32 v6, v16, v17
	v_cvt_pk_bf16_f32 v7, v14, v15
	global_store_dwordx4 v[18:19], v[4:7], off offset:256
	s_and_saveexec_b64 s[8:9], vcc
	s_cbranch_execz .LBB0_428
	s_waitcnt lgkmcnt(0)
	v_add_f32_e32 v2, v2, v3
	v_lshl_add_u32 v3, v222, 4, s42
	ds_write_b32 v3, v2

.LBB0_1484:
	s_or_b64 exec, exec, s[50:51]
	s_lshr_b32 s33, s53, 2
	s_and_b32 s73, s53, 3
	v_mov_b32_e32 v130, v0
	s_lshl_b32 s7, s33, 4
	s_lshl_b32 s11, s73, 1
	s_barrier
	s_or_b32 s18, s7, s11
	v_ashrrev_i32_e32 v131, 31, v130
	s_ashr_i32 s7, s6, 31
	v_lshl_add_u64 v[130:131], v[130:131], 4, s[68:69]
	s_or_b32 s44, s18, 8
	s_lshl_b64 s[20:21], s[6:7], 17
	s_mov_b32 s19, s45
	s_lshl_b64 s[50:51], s[44:45], 12
	v_lshl_add_u64 v[132:133], v[130:131], 0, s[20:21]
	s_lshl_b64 s[86:87], s[18:19], 12
	s_or_b32 s44, s18, 1
	v_lshl_add_u64 v[134:135], v[132:133], 0, s[86:87]
	s_add_u32 s88, s86, 8
	s_addc_u32 s89, s87, 0
	s_or_b32 s44, s18, 9
	s_or_b32 s18, s6, 1
	global_load_dwordx2 v[154:155], v[134:135], off sc1
	v_lshl_add_u64 v[134:135], v[132:133], 0, s[88:89]
	s_add_u32 s90, s50, 8
	s_addc_u32 s91, s51, 0
	s_ashr_i32 s19, s18, 31
	global_load_dwordx2 v[156:157], v[134:135], off sc1
	v_lshl_add_u64 v[134:135], v[132:133], 0, s[50:51]
	v_lshl_add_u64 v[132:133], v[132:133], 0, s[90:91]
	s_lshl_b64 s[18:19], s[18:19], 17
	global_load_dwordx2 v[158:159], v[134:135], off sc1
	global_load_dwordx2 v[160:161], v[132:133], off sc1
	v_lshl_add_u64 v[132:133], v[130:131], 0, s[18:19]
	v_lshl_add_u64 v[134:135], v[132:133], 0, s[86:87]
	s_or_b32 s18, s6, 2
	global_load_dwordx2 v[162:163], v[134:135], off sc1
	v_lshl_add_u64 v[134:135], v[132:133], 0, s[88:89]
	s_ashr_i32 s19, s18, 31
	global_load_dwordx2 v[164:165], v[134:135], off sc1
	v_lshl_add_u64 v[134:135], v[132:133], 0, s[50:51]
	v_lshl_add_u64 v[132:133], v[132:133], 0, s[90:91]
	s_lshl_b64 s[18:19], s[18:19], 17
	global_load_dwordx2 v[166:167], v[134:135], off sc1
	global_load_dwordx2 v[168:169], v[132:133], off sc1
	v_lshl_add_u64 v[132:133], v[130:131], 0, s[18:19]
	v_lshl_add_u64 v[134:135], v[132:133], 0, s[86:87]
	s_or_b32 s18, s6, 3
	global_load_dwordx2 v[170:171], v[134:135], off sc1
	v_lshl_add_u64 v[134:135], v[132:133], 0, s[88:89]
	s_ashr_i32 s19, s18, 31
	global_load_dwordx2 v[172:173], v[134:135], off sc1
	v_lshl_add_u64 v[134:135], v[132:133], 0, s[50:51]
	v_lshl_add_u64 v[132:133], v[132:133], 0, s[90:91]
	s_lshl_b64 s[18:19], s[18:19], 17
	global_load_dwordx2 v[174:175], v[134:135], off sc1
	global_load_dwordx2 v[176:177], v[132:133], off sc1
	v_lshl_add_u64 v[132:133], v[130:131], 0, s[18:19]
	v_lshl_add_u64 v[134:135], v[132:133], 0, s[86:87]
	s_or_b32 s18, s6, 4
	global_load_dwordx2 v[178:179], v[134:135], off sc1
	v_lshl_add_u64 v[134:135], v[132:133], 0, s[88:89]
	s_ashr_i32 s19, s18, 31
	global_load_dwordx2 v[180:181], v[134:135], off sc1
	v_lshl_add_u64 v[134:135], v[132:133], 0, s[50:51]
	v_lshl_add_u64 v[132:133], v[132:133], 0, s[90:91]
	s_lshl_b64 s[18:19], s[18:19], 17
	global_load_dwordx2 v[182:183], v[134:135], off sc1
	global_load_dwordx2 v[184:185], v[132:133], off sc1
	v_lshl_add_u64 v[132:133], v[130:131], 0, s[18:19]
	v_lshl_add_u64 v[134:135], v[132:133], 0, s[86:87]
	global_load_dwordx2 v[196:197], v[134:135], off sc1
	v_lshl_add_u64 v[134:135], v[132:133], 0, s[88:89]
	global_load_dwordx2 v[198:199], v[134:135], off sc1
	v_lshl_add_u64 v[134:135], v[132:133], 0, s[50:51]
	global_load_dwordx2 v[200:201], v[134:135], off sc1
	s_or_b32 s18, s6, 5
	s_ashr_i32 s19, s18, 31
	v_lshl_add_u64 v[132:133], v[132:133], 0, s[90:91]
	s_lshl_b64 s[18:19], s[18:19], 17
	global_load_dwordx2 v[202:203], v[132:133], off sc1
	v_lshl_add_u64 v[132:133], v[130:131], 0, s[18:19]
	v_lshl_add_u64 v[134:135], v[132:133], 0, s[86:87]
	global_load_dwordx2 v[152:153], v[134:135], off sc1
	v_lshl_add_u64 v[134:135], v[132:133], 0, s[88:89]
	global_load_dwordx2 v[150:151], v[134:135], off sc1
	v_lshl_add_u64 v[134:135], v[132:133], 0, s[50:51]
	global_load_dwordx2 v[148:149], v[134:135], off sc1
	v_lshl_add_u64 v[132:133], v[132:133], 0, s[90:91]
	global_load_dwordx2 v[144:145], v[132:133], off sc1
	s_or_b32 s18, s6, 6
	s_ashr_i32 s19, s18, 31
	s_lshl_b64 s[18:19], s[18:19], 17
	v_lshl_add_u64 v[132:133], v[130:131], 0, s[18:19]
	v_lshl_add_u64 v[134:135], v[132:133], 0, s[86:87]
	s_or_b32 s6, s6, 7
	global_load_dwordx2 v[146:147], v[134:135], off sc1
	v_lshl_add_u64 v[134:135], v[132:133], 0, s[88:89]
	s_ashr_i32 s7, s6, 31
	global_load_dwordx2 v[142:143], v[134:135], off sc1
	v_lshl_add_u64 v[134:135], v[132:133], 0, s[50:51]
	s_lshl_b64 s[6:7], s[6:7], 17
	global_load_dwordx2 v[140:141], v[134:135], off sc1
	s_waitcnt vmcnt(26)
	v_lshlrev_b32_e32 v204, 16, v154
	v_and_b32_e32 v205, 0xffff0000, v154
	v_lshlrev_b32_e32 v154, 16, v155
	v_and_b32_e32 v155, 0xffff0000, v155
	v_pk_add_f32 v[154:155], v[154:155], 0 op_sel_hi:[1,0]
	s_waitcnt vmcnt(25)
	v_lshlrev_b32_e32 v206, 16, v156
	v_and_b32_e32 v207, 0xffff0000, v156
	v_lshlrev_b32_e32 v156, 16, v157
	v_and_b32_e32 v157, 0xffff0000, v157
	v_pk_add_f32 v[156:157], v[156:157], 0 op_sel_hi:[1,0]
	s_waitcnt vmcnt(24)
	v_lshlrev_b32_e32 v208, 16, v158
	v_and_b32_e32 v209, 0xffff0000, v158
	v_lshlrev_b32_e32 v158, 16, v159
	s_waitcnt vmcnt(22)
	v_lshlrev_b32_e32 v222, 16, v162
	v_and_b32_e32 v223, 0xffff0000, v162
	v_lshlrev_b32_e32 v162, 16, v163
	v_and_b32_e32 v163, 0xffff0000, v163
	v_and_b32_e32 v159, 0xffff0000, v159
	v_pk_add_f32 v[154:155], v[154:155], v[162:163]
	s_waitcnt vmcnt(21)
	v_lshlrev_b32_e32 v162, 16, v164
	v_and_b32_e32 v163, 0xffff0000, v164
	v_lshlrev_b32_e32 v164, 16, v165
	v_and_b32_e32 v165, 0xffff0000, v165
	v_pk_add_f32 v[158:159], v[158:159], 0 op_sel_hi:[1,0]
	v_lshlrev_b32_e32 v210, 16, v160
	v_and_b32_e32 v211, 0xffff0000, v160
	v_lshlrev_b32_e32 v160, 16, v161
	v_and_b32_e32 v161, 0xffff0000, v161
	v_pk_add_f32 v[156:157], v[156:157], v[164:165]
	s_waitcnt vmcnt(20)
	v_lshlrev_b32_e32 v164, 16, v166
	v_and_b32_e32 v165, 0xffff0000, v166
	v_lshlrev_b32_e32 v166, 16, v167
	v_and_b32_e32 v167, 0xffff0000, v167
	v_pk_add_f32 v[160:161], v[160:161], 0 op_sel_hi:[1,0]
	v_pk_add_f32 v[158:159], v[158:159], v[166:167]
	s_waitcnt vmcnt(19)
	v_lshlrev_b32_e32 v166, 16, v168
	v_and_b32_e32 v167, 0xffff0000, v168
	v_lshlrev_b32_e32 v168, 16, v169
	v_and_b32_e32 v169, 0xffff0000, v169
	v_pk_add_f32 v[160:161], v[160:161], v[168:169]
	s_waitcnt vmcnt(18)
	v_lshlrev_b32_e32 v168, 16, v170
	v_and_b32_e32 v169, 0xffff0000, v170
	v_lshlrev_b32_e32 v170, 16, v171
	v_and_b32_e32 v171, 0xffff0000, v171
	v_pk_add_f32 v[154:155], v[154:155], v[170:171]
	s_waitcnt vmcnt(17)
	v_lshlrev_b32_e32 v170, 16, v172
	v_and_b32_e32 v171, 0xffff0000, v172
	v_lshlrev_b32_e32 v172, 16, v173
	v_and_b32_e32 v173, 0xffff0000, v173
	v_pk_add_f32 v[206:207], v[206:207], 0 op_sel_hi:[1,0]
	v_pk_add_f32 v[156:157], v[156:157], v[172:173]
	s_waitcnt vmcnt(16)
	v_lshlrev_b32_e32 v172, 16, v175
	v_and_b32_e32 v173, 0xffff0000, v175
	v_pk_add_f32 v[208:209], v[208:209], 0 op_sel_hi:[1,0]
	v_pk_add_f32 v[162:163], v[206:207], v[162:163]
	v_pk_add_f32 v[158:159], v[158:159], v[172:173]
	s_waitcnt vmcnt(15)
	v_lshlrev_b32_e32 v172, 16, v177
	v_and_b32_e32 v173, 0xffff0000, v177
	v_pk_add_f32 v[204:205], v[204:205], 0 op_sel_hi:[1,0]
	v_pk_add_f32 v[210:211], v[210:211], 0 op_sel_hi:[1,0]
	v_pk_add_f32 v[164:165], v[208:209], v[164:165]
	v_pk_add_f32 v[162:163], v[162:163], v[170:171]
	v_lshlrev_b32_e32 v170, 16, v174
	v_and_b32_e32 v171, 0xffff0000, v174
	v_pk_add_f32 v[160:161], v[160:161], v[172:173]
	s_waitcnt vmcnt(14)
	v_lshlrev_b32_e32 v172, 16, v179
	v_and_b32_e32 v173, 0xffff0000, v179
	v_pk_add_f32 v[204:205], v[204:205], v[222:223]
	v_pk_add_f32 v[166:167], v[210:211], v[166:167]
	v_pk_add_f32 v[164:165], v[164:165], v[170:171]
	v_lshlrev_b32_e32 v170, 16, v176
	v_and_b32_e32 v171, 0xffff0000, v176
	v_pk_add_f32 v[154:155], v[154:155], v[172:173]
	s_waitcnt vmcnt(13)
	v_lshlrev_b32_e32 v172, 16, v181
	v_and_b32_e32 v173, 0xffff0000, v181
	v_pk_add_f32 v[168:169], v[204:205], v[168:169]
	v_pk_add_f32 v[166:167], v[166:167], v[170:171]
	v_lshlrev_b32_e32 v170, 16, v178
	v_and_b32_e32 v171, 0xffff0000, v178
	v_pk_add_f32 v[156:157], v[156:157], v[172:173]
	s_waitcnt vmcnt(12)
	v_lshlrev_b32_e32 v172, 16, v183
	v_and_b32_e32 v173, 0xffff0000, v183
	v_pk_add_f32 v[168:169], v[168:169], v[170:171]
	v_lshlrev_b32_e32 v170, 16, v180
	v_and_b32_e32 v171, 0xffff0000, v180
	v_pk_add_f32 v[158:159], v[158:159], v[172:173]
	s_waitcnt vmcnt(11)
	v_lshlrev_b32_e32 v172, 16, v185
	v_and_b32_e32 v173, 0xffff0000, v185
	v_lshl_add_u64 v[132:133], v[132:133], 0, s[90:91]
	v_lshl_add_u64 v[130:131], v[130:131], 0, s[6:7]
	v_pk_add_f32 v[162:163], v[162:163], v[170:171]
	v_lshlrev_b32_e32 v170, 16, v182
	v_and_b32_e32 v171, 0xffff0000, v182
	v_pk_add_f32 v[160:161], v[160:161], v[172:173]
	s_waitcnt vmcnt(10)
	v_lshlrev_b32_e32 v172, 16, v197
	v_and_b32_e32 v173, 0xffff0000, v197
	global_load_dwordx2 v[136:137], v[132:133], off sc1
	v_lshl_add_u64 v[132:133], v[130:131], 0, s[86:87]
	v_pk_add_f32 v[164:165], v[164:165], v[170:171]
	v_lshlrev_b32_e32 v170, 16, v184
	v_and_b32_e32 v171, 0xffff0000, v184
	v_pk_add_f32 v[172:173], v[154:155], v[172:173]
	s_waitcnt vmcnt(10)
	v_lshlrev_b32_e32 v154, 16, v198
	v_and_b32_e32 v155, 0xffff0000, v198
	global_load_dwordx2 v[138:139], v[132:133], off sc1
	v_lshl_add_u64 v[132:133], v[130:131], 0, s[88:89]
	v_pk_add_f32 v[166:167], v[166:167], v[170:171]
	v_lshlrev_b32_e32 v170, 16, v196
	v_and_b32_e32 v171, 0xffff0000, v196
	v_pk_add_f32 v[162:163], v[162:163], v[154:155]
	s_waitcnt vmcnt(10)
	v_lshlrev_b32_e32 v154, 16, v200
	v_and_b32_e32 v155, 0xffff0000, v200
	s_lshl_b32 s11, s24, 8
	v_lshl_add_u32 v182, s33, 7, v214
	global_load_dwordx2 v[134:135], v[132:133], off sc1
	v_lshl_add_u64 v[132:133], v[130:131], 0, s[50:51]
	v_pk_add_f32 v[168:169], v[168:169], v[170:171]
	v_lshlrev_b32_e32 v170, 16, v199
	v_and_b32_e32 v171, 0xffff0000, v199
	v_pk_add_f32 v[164:165], v[164:165], v[154:155]
	s_lshl_b32 s6, s73, 4
	v_add_u32_e32 v154, s11, v182
	global_load_dwordx2 v[132:133], v[132:133], off sc1
	v_lshl_add_u64 v[130:131], v[130:131], 0, s[90:91]
	v_pk_add_f32 v[170:171], v[156:157], v[170:171]
	v_lshlrev_b32_e32 v156, 16, v201
	v_and_b32_e32 v157, 0xffff0000, v201
	v_or_b32_e32 v154, s6, v154
	global_load_dwordx2 v[130:131], v[130:131], off sc1
	v_pk_add_f32 v[158:159], v[158:159], v[156:157]
	v_lshl_or_b32 v156, s10, 8, v217
	v_ashrrev_i32_e32 v155, 31, v154
	v_readlane_b32 s18, v254, 62
	v_ashrrev_i32_e32 v157, 31, v156
	v_lshlrev_b64 v[154:155], 11, v[154:155]
	v_readlane_b32 s19, v254, 63
	v_lshlrev_b64 v[178:179], 1, v[156:157]
	s_waitcnt vmcnt(12)
	v_lshlrev_b32_e32 v174, 16, v202
	v_lshl_add_u64 v[154:155], s[18:19], 0, v[154:155]
	v_lshl_add_u64 v[180:181], v[154:155], 0, v[178:179]
	global_load_dwordx4 v[154:157], v[180:181], off
	v_and_b32_e32 v175, 0xffff0000, v202
	v_pk_add_f32 v[166:167], v[166:167], v[174:175]
	s_waitcnt vmcnt(12)
	v_lshlrev_b32_e32 v174, 16, v152
	v_and_b32_e32 v175, 0xffff0000, v152
	v_lshlrev_b32_e32 v152, 16, v153
	v_and_b32_e32 v153, 0xffff0000, v153
	v_pk_add_f32 v[152:153], v[172:173], v[152:153]
	s_waitcnt vmcnt(11)
	v_lshlrev_b32_e32 v172, 16, v150
	v_and_b32_e32 v173, 0xffff0000, v150
	v_lshlrev_b32_e32 v150, 16, v151
	v_and_b32_e32 v151, 0xffff0000, v151
	v_pk_add_f32 v[170:171], v[170:171], v[150:151]
	s_waitcnt vmcnt(10)
	v_lshlrev_b32_e32 v150, 16, v148
	v_and_b32_e32 v151, 0xffff0000, v148
	v_lshlrev_b32_e32 v148, 16, v149
	v_and_b32_e32 v149, 0xffff0000, v149
	v_pk_add_f32 v[158:159], v[158:159], v[148:149]
	s_waitcnt vmcnt(9)
	v_lshlrev_b32_e32 v148, 16, v144
	v_and_b32_e32 v149, 0xffff0000, v144
	v_pk_add_f32 v[164:165], v[164:165], v[150:151]
	v_pk_add_f32 v[166:167], v[166:167], v[148:149]
	global_load_dwordx4 v[148:151], v[180:181], off offset:256
	v_lshlrev_b32_e32 v176, 16, v203
	v_and_b32_e32 v177, 0xffff0000, v203
	v_pk_add_f32 v[160:161], v[160:161], v[176:177]
	v_lshlrev_b32_e32 v144, 16, v145
	v_and_b32_e32 v145, 0xffff0000, v145
	v_pk_add_f32 v[168:169], v[168:169], v[174:175]
	v_pk_add_f32 v[144:145], v[160:161], v[144:145]
	s_waitcnt vmcnt(9)
	v_lshlrev_b32_e32 v160, 16, v146
	v_and_b32_e32 v161, 0xffff0000, v146
	v_lshlrev_b32_e32 v146, 16, v147
	v_and_b32_e32 v147, 0xffff0000, v147
	v_pk_add_f32 v[162:163], v[162:163], v[172:173]
	v_pk_add_f32 v[146:147], v[152:153], v[146:147]
	v_pk_add_f32 v[152:153], v[168:169], v[160:161]
	s_waitcnt vmcnt(8)
	v_lshlrev_b32_e32 v160, 16, v142
	v_and_b32_e32 v161, 0xffff0000, v142
	v_pk_add_f32 v[160:161], v[162:163], v[160:161]
	s_waitcnt vmcnt(7)
	v_lshlrev_b32_e32 v162, 16, v140
	v_and_b32_e32 v163, 0xffff0000, v140
	v_lshlrev_b32_e32 v140, 16, v141
	v_and_b32_e32 v141, 0xffff0000, v141
	v_pk_add_f32 v[140:141], v[158:159], v[140:141]
	v_pk_add_f32 v[158:159], v[164:165], v[162:163]
	s_waitcnt vmcnt(6)
	v_lshlrev_b32_e32 v162, 16, v136
	v_and_b32_e32 v163, 0xffff0000, v136
	v_lshlrev_b32_e32 v136, 16, v137
	v_and_b32_e32 v137, 0xffff0000, v137
	v_lshlrev_b32_e32 v142, 16, v143
	v_and_b32_e32 v143, 0xffff0000, v143
	v_pk_add_f32 v[136:137], v[144:145], v[136:137]
	v_pk_add_f32 v[144:145], v[166:167], v[162:163]
	s_waitcnt vmcnt(5)
	v_lshlrev_b32_e32 v162, 16, v138
	v_and_b32_e32 v163, 0xffff0000, v138
	v_lshlrev_b32_e32 v138, 16, v139
	v_and_b32_e32 v139, 0xffff0000, v139
	v_pk_add_f32 v[142:143], v[170:171], v[142:143]
	v_pk_add_f32 v[138:139], v[146:147], v[138:139]
	s_waitcnt vmcnt(4)
	v_lshlrev_b32_e32 v146, 16, v134
	v_and_b32_e32 v147, 0xffff0000, v134
	v_lshlrev_b32_e32 v134, 16, v135
	v_and_b32_e32 v135, 0xffff0000, v135
	v_pk_add_f32 v[134:135], v[142:143], v[134:135]
	s_waitcnt vmcnt(3)
	v_lshlrev_b32_e32 v142, 16, v132
	v_and_b32_e32 v143, 0xffff0000, v132
	v_lshlrev_b32_e32 v132, 16, v133
	v_and_b32_e32 v133, 0xffff0000, v133
	v_pk_add_f32 v[140:141], v[140:141], v[132:133]
	s_waitcnt vmcnt(2)
	v_lshlrev_b32_e32 v132, 16, v130
	v_and_b32_e32 v133, 0xffff0000, v130
	v_lshlrev_b32_e32 v130, 16, v131
	v_and_b32_e32 v131, 0xffff0000, v131
	v_pk_add_f32 v[136:137], v[136:137], v[130:131]
	v_or_b32_e32 v130, s6, v182
	v_pk_add_f32 v[144:145], v[144:145], v[132:133]
	v_add_u32_e32 v132, s11, v130
	v_ashrrev_i32_e32 v133, 31, v132
	v_pk_add_f32 v[152:153], v[152:153], v[162:163]
	v_pk_add_f32 v[142:143], v[158:159], v[142:143]
	v_lshlrev_b64 v[158:159], 11, v[132:133]
	s_waitcnt vmcnt(1)
	v_lshlrev_b32_e32 v132, 16, v154
	v_and_b32_e32 v133, 0xffff0000, v154
	v_lshlrev_b32_e32 v154, 16, v155
	v_and_b32_e32 v155, 0xffff0000, v155
	v_pk_add_f32 v[146:147], v[160:161], v[146:147]
	v_lshlrev_b32_e32 v160, 16, v156
	v_and_b32_e32 v161, 0xffff0000, v156
	v_lshlrev_b32_e32 v156, 16, v157
	v_and_b32_e32 v157, 0xffff0000, v157
	v_pk_add_f32 v[138:139], v[138:139], v[154:155]
	v_pk_add_f32 v[132:133], v[152:153], v[132:133]
	v_pk_add_f32 v[152:153], v[134:135], v[156:157]
	v_pk_add_f32 v[134:135], v[146:147], v[160:161]
	v_mul_f32_e32 v131, v133, v133
	v_mul_f32_e32 v146, v139, v139
	v_fmac_f32_e32 v131, v132, v132
	v_fmac_f32_e32 v146, v138, v138
	v_add_f32_e32 v131, v131, v146
	v_mul_f32_e32 v146, v135, v135
	v_mul_f32_e32 v147, v153, v153
	v_fmac_f32_e32 v146, v134, v134
	v_fmac_f32_e32 v147, v152, v152
	v_add_f32_e32 v146, v146, v147
	v_add_f32_e32 v131, v131, v146
	v_cvt_pk_bf16_f32 v132, v132, v133
	v_cvt_pk_bf16_f32 v133, v138, v139
	s_waitcnt vmcnt(0)
	v_lshlrev_b32_e32 v138, 16, v148
	v_and_b32_e32 v139, 0xffff0000, v148
	v_lshlrev_b32_e32 v146, 16, v149
	v_and_b32_e32 v147, 0xffff0000, v149
	v_lshlrev_b32_e32 v148, 16, v150
	v_and_b32_e32 v149, 0xffff0000, v150
	v_lshlrev_b32_e32 v150, 16, v151
	v_and_b32_e32 v151, 0xffff0000, v151
	v_pk_add_f32 v[140:141], v[140:141], v[146:147]
	v_pk_add_f32 v[138:139], v[142:143], v[138:139]
	v_pk_add_f32 v[142:143], v[136:137], v[150:151]
	v_pk_add_f32 v[136:137], v[144:145], v[148:149]
	v_mul_f32_e32 v144, v139, v139
	v_mul_f32_e32 v145, v141, v141
	v_fmac_f32_e32 v144, v138, v138
	v_fmac_f32_e32 v145, v140, v140
	v_add_f32_e32 v144, v144, v145
	v_mul_f32_e32 v145, v137, v137
	v_mul_f32_e32 v146, v143, v143
	v_fmac_f32_e32 v145, v136, v136
	v_fmac_f32_e32 v146, v142, v142
	v_add_f32_e32 v145, v145, v146
	v_add_f32_e32 v144, v144, v145
	v_and_b32_e32 v145, 64, v221
	v_add_f32_e32 v131, v131, v144
	v_xor_b32_e32 v144, 16, v221
	v_add_u32_e32 v146, 64, v145
	v_cmp_lt_i32_e32 vcc, v144, v146
	v_cvt_pk_bf16_f32 v134, v134, v135
	v_cvt_pk_bf16_f32 v135, v152, v153
	s_nop 1
	v_cndmask_b32_e32 v144, v221, v144, vcc
	v_lshlrev_b32_e32 v144, 2, v144
	v_mov_b32_e32 v147, v131
	s_nop 1
	v_permlane16_swap_b32_e32 v131, v147
	v_lshl_add_u64 v[144:145], s[42:43], 0, v[158:159]
	v_lshl_add_u64 v[144:145], v[144:145], 0, v[178:179]
	global_store_dwordx4 v[144:145], v[132:135], off
	s_waitcnt lgkmcnt(0)
	v_add_f32_e32 v131, v131, v147
	v_xor_b32_e32 v132, 32, v221
	v_cmp_lt_i32_e32 vcc, v132, v146
	v_cvt_pk_bf16_f32 v134, v138, v139
	v_cvt_pk_bf16_f32 v135, v140, v141
	v_cvt_pk_bf16_f32 v136, v136, v137
	v_cvt_pk_bf16_f32 v137, v142, v143
	global_store_dwordx4 v[144:145], v[134:137], off offset:256
	s_nop 0
	v_cndmask_b32_e32 v132, v221, v132, vcc
	v_lshlrev_b32_e32 v132, 2, v132
	v_mov_b32_e32 v132, v131
	s_nop 1
	v_permlane32_swap_b32_e32 v131, v132
	s_and_saveexec_b64 s[6:7], s[4:5]
	s_cbranch_execz .LBB0_1486
	v_lshl_add_u32 v130, v130, 4, s15
	s_waitcnt lgkmcnt(0)
	v_add_f32_e32 v131, v131, v132
	ds_write_b32 v130, v131

.LBB0_1487:
	s_lshl_b32 s6, s10, 8
	v_mov_b32_e32 v130, v1
	v_mov_b32_e32 v244, v213
	s_or_b32 s6, s6, s12
	s_lshl_b32 s11, s24, 8
	v_add_u32_e32 v229, s97, v130
	v_lshl_add_u32 v196, v244, 3, s6
	v_ashrrev_i32_e32 v197, 31, v196
	v_readlane_b32 s6, v254, 62
	s_waitcnt lgkmcnt(0)
	v_add_u32_e32 v132, s11, v229
	v_lshlrev_b64 v[238:239], 1, v[196:197]
	v_readlane_b32 s7, v254, 63
	v_ashrrev_i32_e32 v133, 31, v132
	v_lshlrev_b64 v[240:241], 11, v[132:133]
	v_lshl_add_u64 v[130:131], s[6:7], 0, v[238:239]
	v_lshl_add_u64 v[132:133], v[130:131], 0, v[240:241]
	global_load_dwordx4 v[230:233], v[132:133], off
	global_load_dwordx4 v[234:237], v[132:133], off offset:256
	v_add_u32_e32 v228, 16, v229
	v_add_u32_e32 v227, 32, v229
	v_add_u32_e32 v226, 48, v229
	v_add_u32_e32 v225, 0x80, v229
	v_add_u32_e32 v224, 0x90, v229
	v_add_u32_e32 v223, 0xa0, v229
	v_add_u32_e32 v222, 0xb0, v229
	v_add_u32_e32 v132, s11, v228
	v_add_u32_e32 v134, s11, v227
	v_add_u32_e32 v136, s11, v226
	v_add_u32_e32 v138, s11, v225
	v_add_u32_e32 v140, s11, v224
	v_add_u32_e32 v142, s11, v223
	v_add_u32_e32 v144, s11, v222
	v_ashrrev_i32_e32 v133, 31, v132
	v_ashrrev_i32_e32 v135, 31, v134
	v_ashrrev_i32_e32 v137, 31, v136
	v_ashrrev_i32_e32 v139, 31, v138
	v_ashrrev_i32_e32 v141, 31, v140
	v_ashrrev_i32_e32 v143, 31, v142
	v_ashrrev_i32_e32 v145, 31, v144
	v_lshlrev_b64 v[210:211], 11, v[132:133]
	v_lshlrev_b64 v[208:209], 11, v[134:135]
	v_lshlrev_b64 v[206:207], 11, v[136:137]
	v_lshlrev_b64 v[204:205], 11, v[138:139]
	v_lshlrev_b64 v[202:203], 11, v[140:141]
	v_lshlrev_b64 v[200:201], 11, v[142:143]
	v_lshlrev_b64 v[198:199], 11, v[144:145]
	v_lshl_add_u64 v[132:133], v[130:131], 0, v[210:211]
	v_lshl_add_u64 v[134:135], v[130:131], 0, v[208:209]
	v_lshl_add_u64 v[136:137], v[130:131], 0, v[206:207]
	v_lshl_add_u64 v[138:139], v[130:131], 0, v[204:205]
	v_lshl_add_u64 v[140:141], v[130:131], 0, v[202:203]
	v_lshl_add_u64 v[242:243], v[130:131], 0, v[200:201]
	v_lshl_add_u64 v[130:131], v[130:131], 0, v[198:199]
	global_load_dwordx4 v[182:185], v[132:133], off
	global_load_dwordx4 v[178:181], v[132:133], off offset:256
	global_load_dwordx4 v[174:177], v[134:135], off
	global_load_dwordx4 v[170:173], v[134:135], off offset:256
	global_load_dwordx4 v[166:169], v[136:137], off
	global_load_dwordx4 v[162:165], v[136:137], off offset:256
	global_load_dwordx4 v[158:161], v[138:139], off
	global_load_dwordx4 v[154:157], v[138:139], off offset:256
	global_load_dwordx4 v[150:153], v[140:141], off
	global_load_dwordx4 v[146:149], v[140:141], off offset:256
	global_load_dwordx4 v[142:145], v[242:243], off
	s_nop 0
	global_load_dwordx4 v[138:141], v[242:243], off offset:256
	global_load_dwordx4 v[134:137], v[130:131], off
	s_nop 0
	global_load_dwordx4 v[130:133], v[130:131], off offset:256
	v_cmp_eq_u32_e32 vcc, 0, v244
	s_waitcnt vmcnt(0)
	v_lshlrev_b32_e32 v242, 16, v230
	v_and_b32_e32 v243, 0xffff0000, v230
	v_lshlrev_b32_e32 v230, 16, v231
	v_and_b32_e32 v231, 0xffff0000, v231
	v_lshlrev_b32_e32 v244, 16, v232
	v_and_b32_e32 v245, 0xffff0000, v232
	v_lshlrev_b32_e32 v232, 16, v233
	v_and_b32_e32 v233, 0xffff0000, v233
	v_pk_add_f32 v[128:129], v[128:129], v[230:231]
	v_pk_add_f32 v[126:127], v[126:127], v[242:243]
	v_pk_add_f32 v[230:231], v[124:125], v[232:233]
	v_pk_add_f32 v[232:233], v[122:123], v[244:245]
	v_mul_f32_e32 v125, v127, v127
	v_mul_f32_e32 v242, v129, v129
	v_mul_f32_e32 v243, v233, v233
	v_mul_f32_e32 v244, v231, v231
	v_fmac_f32_e32 v125, v126, v126
	v_fmac_f32_e32 v242, v128, v128
	v_fmac_f32_e32 v243, v232, v232
	v_fmac_f32_e32 v244, v230, v230
	v_cvt_pk_bf16_f32 v122, v126, v127
	v_add_f32_e32 v125, v125, v242
	v_add_f32_e32 v126, v243, v244
	v_cvt_pk_bf16_f32 v123, v128, v129
	v_add_f32_e32 v242, v125, v126
	v_lshlrev_b32_e32 v126, 16, v234
	v_and_b32_e32 v127, 0xffff0000, v234
	v_lshlrev_b32_e32 v128, 16, v235
	v_and_b32_e32 v129, 0xffff0000, v235
	v_cvt_pk_bf16_f32 v124, v232, v233
	v_cvt_pk_bf16_f32 v125, v230, v231
	v_lshlrev_b32_e32 v230, 16, v236
	v_and_b32_e32 v231, 0xffff0000, v236
	v_pk_add_f32 v[120:121], v[120:121], v[128:129]
	v_pk_add_f32 v[118:119], v[118:119], v[126:127]
	v_lshlrev_b32_e32 v232, 16, v237
	v_and_b32_e32 v233, 0xffff0000, v237
	v_pk_add_f32 v[128:129], v[114:115], v[230:231]
	v_mul_f32_e32 v114, v119, v119
	v_mul_f32_e32 v115, v121, v121
	v_pk_add_f32 v[126:127], v[116:117], v[232:233]
	v_fmac_f32_e32 v114, v118, v118
	v_fmac_f32_e32 v115, v120, v120
	v_add_f32_e32 v114, v114, v115
	v_mul_f32_e32 v115, v129, v129
	v_mul_f32_e32 v116, v127, v127
	v_fmac_f32_e32 v115, v128, v128
	v_fmac_f32_e32 v116, v126, v126
	v_add_f32_e32 v115, v115, v116
	v_add_f32_e32 v114, v114, v115
	v_and_b32_e32 v116, 64, v221
	v_add_f32_e32 v115, v242, v114
	v_xor_b32_e32 v114, 16, v221
	v_add_u32_e32 v232, 64, v116
	v_cmp_lt_i32_e64 s[6:7], v114, v232
	v_lshl_add_u64 v[116:117], s[42:43], 0, v[240:241]
	v_lshl_add_u64 v[230:231], v[116:117], 0, v[238:239]
	v_cndmask_b32_e64 v114, v221, v114, s[6:7]
	v_lshlrev_b32_e32 v114, 2, v114
	v_mov_b32_e32 v233, v115
	s_nop 1
	v_permlane16_swap_b32_e32 v115, v233
	global_store_dwordx4 v[230:231], v[122:125], off
	v_cvt_pk_bf16_f32 v118, v118, v119
	v_cvt_pk_bf16_f32 v119, v120, v121
	v_cvt_pk_bf16_f32 v120, v128, v129
	s_waitcnt lgkmcnt(0)
	v_add_f32_e32 v116, v115, v233
	v_xor_b32_e32 v115, 32, v221
	v_cmp_lt_i32_e64 s[6:7], v115, v232
	v_cvt_pk_bf16_f32 v121, v126, v127
	global_store_dwordx4 v[230:231], v[118:121], off offset:256
	s_nop 0
	v_cndmask_b32_e64 v115, v221, v115, s[6:7]
	v_lshlrev_b32_e32 v115, 2, v115
	v_mov_b32_e32 v117, v116
	s_nop 1
	v_permlane32_swap_b32_e32 v116, v117
	s_and_saveexec_b64 s[6:7], vcc
	s_cbranch_execz .LBB0_1489
	s_waitcnt lgkmcnt(0)
	v_add_f32_e32 v116, v116, v117
	v_lshl_add_u32 v117, v229, 4, s15
	ds_write_b32 v117, v116
.LBB0_1489:
	s_or_b64 exec, exec, s[6:7]
	v_lshlrev_b32_e32 v116, 16, v182
	s_waitcnt lgkmcnt(0)
	v_and_b32_e32 v117, 0xffff0000, v182
	v_lshlrev_b32_e32 v118, 16, v183
	v_and_b32_e32 v119, 0xffff0000, v183
	v_lshlrev_b32_e32 v120, 16, v184
	v_and_b32_e32 v121, 0xffff0000, v184
	v_lshlrev_b32_e32 v122, 16, v185
	v_and_b32_e32 v123, 0xffff0000, v185
	v_pk_add_f32 v[112:113], v[112:113], v[118:119]
	v_pk_add_f32 v[110:111], v[110:111], v[116:117]
	v_pk_add_f32 v[116:117], v[108:109], v[122:123]
	v_pk_add_f32 v[108:109], v[106:107], v[120:121]
	v_mul_f32_e32 v106, v111, v111
	v_mul_f32_e32 v107, v113, v113
	v_fmac_f32_e32 v106, v110, v110
	v_fmac_f32_e32 v107, v112, v112
	v_add_f32_e32 v106, v106, v107
	v_mul_f32_e32 v107, v109, v109
	v_mul_f32_e32 v118, v117, v117
	v_fmac_f32_e32 v107, v108, v108
	v_fmac_f32_e32 v118, v116, v116
	v_add_f32_e32 v107, v107, v118
	v_add_f32_e32 v120, v106, v107
	v_cvt_pk_bf16_f32 v106, v110, v111
	v_cvt_pk_bf16_f32 v107, v112, v113
	v_lshlrev_b32_e32 v110, 16, v178
	v_and_b32_e32 v111, 0xffff0000, v178
	v_lshlrev_b32_e32 v112, 16, v179
	v_and_b32_e32 v113, 0xffff0000, v179
	v_cvt_pk_bf16_f32 v108, v108, v109
	v_cvt_pk_bf16_f32 v109, v116, v117
	v_lshlrev_b32_e32 v116, 16, v180
	v_and_b32_e32 v117, 0xffff0000, v180
	v_pk_add_f32 v[104:105], v[104:105], v[112:113]
	v_pk_add_f32 v[102:103], v[102:103], v[110:111]
	v_lshlrev_b32_e32 v118, 16, v181
	v_and_b32_e32 v119, 0xffff0000, v181
	v_pk_add_f32 v[112:113], v[98:99], v[116:117]
	v_mul_f32_e32 v98, v103, v103
	v_mul_f32_e32 v99, v105, v105
	v_pk_add_f32 v[110:111], v[100:101], v[118:119]
	v_fmac_f32_e32 v98, v102, v102
	v_fmac_f32_e32 v99, v104, v104
	v_add_f32_e32 v98, v98, v99
	v_mul_f32_e32 v99, v113, v113
	v_mul_f32_e32 v100, v111, v111
	v_fmac_f32_e32 v99, v112, v112
	v_fmac_f32_e32 v100, v110, v110
	v_add_f32_e32 v99, v99, v100
	v_add_f32_e32 v98, v98, v99
	v_add_f32_e32 v101, v120, v98
	v_mov_b32_e32 v118, v101
	s_nop 1
	v_permlane16_swap_b32_e32 v101, v118
	v_lshl_add_u64 v[98:99], s[42:43], 0, v[210:211]
	v_lshl_add_u64 v[116:117], v[196:197], 1, v[98:99]
	global_store_dwordx4 v[116:117], v[106:109], off
	v_cvt_pk_bf16_f32 v100, v102, v103
	s_waitcnt lgkmcnt(0)
	v_add_f32_e32 v98, v101, v118
	v_mov_b32_e32 v99, v98
	s_nop 1
	v_permlane32_swap_b32_e32 v98, v99
	v_cvt_pk_bf16_f32 v101, v104, v105
	v_cvt_pk_bf16_f32 v102, v112, v113
	v_cvt_pk_bf16_f32 v103, v110, v111
	global_store_dwordx4 v[116:117], v[100:103], off offset:256
	s_and_saveexec_b64 s[6:7], vcc
	s_cbranch_execz .LBB0_1491
	s_waitcnt lgkmcnt(0)
	v_add_f32_e32 v98, v98, v99
	v_lshl_add_u32 v99, v228, 4, s15
	ds_write_b32 v99, v98
.LBB0_1491:
	s_or_b64 exec, exec, s[6:7]
	v_lshlrev_b32_e32 v98, 16, v174
	s_waitcnt lgkmcnt(0)
	v_and_b32_e32 v99, 0xffff0000, v174
	v_lshlrev_b32_e32 v100, 16, v175
	v_and_b32_e32 v101, 0xffff0000, v175
	v_lshlrev_b32_e32 v102, 16, v176
	v_and_b32_e32 v103, 0xffff0000, v176
	v_lshlrev_b32_e32 v104, 16, v177
	v_and_b32_e32 v105, 0xffff0000, v177
	v_pk_add_f32 v[96:97], v[96:97], v[100:101]
	v_pk_add_f32 v[94:95], v[94:95], v[98:99]
	v_pk_add_f32 v[98:99], v[92:93], v[104:105]
	v_pk_add_f32 v[92:93], v[90:91], v[102:103]
	v_mul_f32_e32 v90, v95, v95
	v_mul_f32_e32 v91, v97, v97
	v_fmac_f32_e32 v90, v94, v94
	v_fmac_f32_e32 v91, v96, v96
	v_add_f32_e32 v90, v90, v91
	v_mul_f32_e32 v91, v93, v93
	v_mul_f32_e32 v100, v99, v99
	v_fmac_f32_e32 v91, v92, v92
	v_fmac_f32_e32 v100, v98, v98
	v_add_f32_e32 v91, v91, v100
	v_add_f32_e32 v102, v90, v91
	v_cvt_pk_bf16_f32 v90, v94, v95
	v_cvt_pk_bf16_f32 v91, v96, v97
	v_lshlrev_b32_e32 v94, 16, v170
	v_and_b32_e32 v95, 0xffff0000, v170
	v_lshlrev_b32_e32 v96, 16, v171
	v_and_b32_e32 v97, 0xffff0000, v171
	v_cvt_pk_bf16_f32 v92, v92, v93
	v_cvt_pk_bf16_f32 v93, v98, v99
	v_lshlrev_b32_e32 v98, 16, v172
	v_and_b32_e32 v99, 0xffff0000, v172
	v_pk_add_f32 v[88:89], v[88:89], v[96:97]
	v_pk_add_f32 v[86:87], v[86:87], v[94:95]
	v_lshlrev_b32_e32 v100, 16, v173
	v_and_b32_e32 v101, 0xffff0000, v173
	v_pk_add_f32 v[96:97], v[82:83], v[98:99]
	v_mul_f32_e32 v82, v87, v87
	v_mul_f32_e32 v83, v89, v89
	v_pk_add_f32 v[94:95], v[84:85], v[100:101]
	v_fmac_f32_e32 v82, v86, v86
	v_fmac_f32_e32 v83, v88, v88
	v_add_f32_e32 v82, v82, v83
	v_mul_f32_e32 v83, v97, v97
	v_mul_f32_e32 v84, v95, v95
	v_fmac_f32_e32 v83, v96, v96
	v_fmac_f32_e32 v84, v94, v94
	v_add_f32_e32 v83, v83, v84
	v_add_f32_e32 v82, v82, v83
	v_add_f32_e32 v85, v102, v82
	v_mov_b32_e32 v100, v85
	s_nop 1
	v_permlane16_swap_b32_e32 v85, v100
	v_lshl_add_u64 v[82:83], s[42:43], 0, v[208:209]
	v_lshl_add_u64 v[98:99], v[196:197], 1, v[82:83]
	global_store_dwordx4 v[98:99], v[90:93], off
	v_cvt_pk_bf16_f32 v84, v86, v87
	s_waitcnt lgkmcnt(0)
	v_add_f32_e32 v82, v85, v100
	v_mov_b32_e32 v83, v82
	s_nop 1
	v_permlane32_swap_b32_e32 v82, v83
	v_cvt_pk_bf16_f32 v85, v88, v89
	v_cvt_pk_bf16_f32 v86, v96, v97
	v_cvt_pk_bf16_f32 v87, v94, v95
	global_store_dwordx4 v[98:99], v[84:87], off offset:256
	s_and_saveexec_b64 s[6:7], vcc
	s_cbranch_execz .LBB0_1493
	s_waitcnt lgkmcnt(0)
	v_add_f32_e32 v82, v82, v83
	v_lshl_add_u32 v83, v227, 4, s15
	ds_write_b32 v83, v82
.LBB0_1493:
	s_or_b64 exec, exec, s[6:7]
	v_lshlrev_b32_e32 v82, 16, v166
	s_waitcnt lgkmcnt(0)
	v_and_b32_e32 v83, 0xffff0000, v166
	v_lshlrev_b32_e32 v84, 16, v167
	v_and_b32_e32 v85, 0xffff0000, v167
	v_lshlrev_b32_e32 v86, 16, v168
	v_and_b32_e32 v87, 0xffff0000, v168
	v_lshlrev_b32_e32 v88, 16, v169
	v_and_b32_e32 v89, 0xffff0000, v169
	v_pk_add_f32 v[80:81], v[80:81], v[84:85]
	v_pk_add_f32 v[78:79], v[78:79], v[82:83]
	v_pk_add_f32 v[82:83], v[76:77], v[88:89]
	v_pk_add_f32 v[76:77], v[74:75], v[86:87]
	v_mul_f32_e32 v74, v79, v79
	v_mul_f32_e32 v75, v81, v81
	v_fmac_f32_e32 v74, v78, v78
	v_fmac_f32_e32 v75, v80, v80
	v_add_f32_e32 v74, v74, v75
	v_mul_f32_e32 v75, v77, v77
	v_mul_f32_e32 v84, v83, v83
	v_fmac_f32_e32 v75, v76, v76
	v_fmac_f32_e32 v84, v82, v82
	v_add_f32_e32 v75, v75, v84
	v_add_f32_e32 v86, v74, v75
	v_cvt_pk_bf16_f32 v74, v78, v79
	v_cvt_pk_bf16_f32 v75, v80, v81
	v_lshlrev_b32_e32 v78, 16, v162
	v_and_b32_e32 v79, 0xffff0000, v162
	v_lshlrev_b32_e32 v80, 16, v163
	v_and_b32_e32 v81, 0xffff0000, v163
	v_cvt_pk_bf16_f32 v76, v76, v77
	v_cvt_pk_bf16_f32 v77, v82, v83
	v_lshlrev_b32_e32 v82, 16, v164
	v_and_b32_e32 v83, 0xffff0000, v164
	v_pk_add_f32 v[72:73], v[72:73], v[80:81]
	v_pk_add_f32 v[70:71], v[70:71], v[78:79]
	v_lshlrev_b32_e32 v84, 16, v165
	v_and_b32_e32 v85, 0xffff0000, v165
	v_pk_add_f32 v[80:81], v[66:67], v[82:83]
	v_mul_f32_e32 v66, v71, v71
	v_mul_f32_e32 v67, v73, v73
	v_pk_add_f32 v[78:79], v[68:69], v[84:85]
	v_fmac_f32_e32 v66, v70, v70
	v_fmac_f32_e32 v67, v72, v72
	v_add_f32_e32 v66, v66, v67
	v_mul_f32_e32 v67, v81, v81
	v_mul_f32_e32 v68, v79, v79
	v_fmac_f32_e32 v67, v80, v80
	v_fmac_f32_e32 v68, v78, v78
	v_add_f32_e32 v67, v67, v68
	v_add_f32_e32 v66, v66, v67
	v_add_f32_e32 v69, v86, v66
	v_mov_b32_e32 v84, v69
	s_nop 1
	v_permlane16_swap_b32_e32 v69, v84
	v_lshl_add_u64 v[66:67], s[42:43], 0, v[206:207]
	v_lshl_add_u64 v[82:83], v[196:197], 1, v[66:67]
	global_store_dwordx4 v[82:83], v[74:77], off
	v_cvt_pk_bf16_f32 v68, v70, v71
	s_waitcnt lgkmcnt(0)
	v_add_f32_e32 v66, v69, v84
	v_mov_b32_e32 v67, v66
	s_nop 1
	v_permlane32_swap_b32_e32 v66, v67
	v_cvt_pk_bf16_f32 v69, v72, v73
	v_cvt_pk_bf16_f32 v70, v80, v81
	v_cvt_pk_bf16_f32 v71, v78, v79
	global_store_dwordx4 v[82:83], v[68:71], off offset:256
	s_and_saveexec_b64 s[6:7], vcc
	s_cbranch_execz .LBB0_1495
	s_waitcnt lgkmcnt(0)
	v_add_f32_e32 v66, v66, v67
	v_lshl_add_u32 v67, v226, 4, s15
	ds_write_b32 v67, v66
.LBB0_1495:
	s_or_b64 exec, exec, s[6:7]
	v_lshlrev_b32_e32 v66, 16, v158
	s_waitcnt lgkmcnt(0)
	v_and_b32_e32 v67, 0xffff0000, v158
	v_lshlrev_b32_e32 v68, 16, v159
	v_and_b32_e32 v69, 0xffff0000, v159
	v_lshlrev_b32_e32 v70, 16, v160
	v_and_b32_e32 v71, 0xffff0000, v160
	v_lshlrev_b32_e32 v72, 16, v161
	v_and_b32_e32 v73, 0xffff0000, v161
	v_pk_add_f32 v[64:65], v[64:65], v[68:69]
	v_pk_add_f32 v[62:63], v[62:63], v[66:67]
	v_pk_add_f32 v[66:67], v[60:61], v[72:73]
	v_pk_add_f32 v[60:61], v[58:59], v[70:71]
	v_mul_f32_e32 v58, v63, v63
	v_mul_f32_e32 v59, v65, v65
	v_fmac_f32_e32 v58, v62, v62
	v_fmac_f32_e32 v59, v64, v64
	v_add_f32_e32 v58, v58, v59
	v_mul_f32_e32 v59, v61, v61
	v_mul_f32_e32 v68, v67, v67
	v_fmac_f32_e32 v59, v60, v60
	v_fmac_f32_e32 v68, v66, v66
	v_add_f32_e32 v59, v59, v68
	v_add_f32_e32 v70, v58, v59
	v_cvt_pk_bf16_f32 v58, v62, v63
	v_cvt_pk_bf16_f32 v59, v64, v65
	v_lshlrev_b32_e32 v62, 16, v154
	v_and_b32_e32 v63, 0xffff0000, v154
	v_lshlrev_b32_e32 v64, 16, v155
	v_and_b32_e32 v65, 0xffff0000, v155
	v_cvt_pk_bf16_f32 v60, v60, v61
	v_cvt_pk_bf16_f32 v61, v66, v67
	v_lshlrev_b32_e32 v66, 16, v156
	v_and_b32_e32 v67, 0xffff0000, v156
	v_pk_add_f32 v[56:57], v[56:57], v[64:65]
	v_pk_add_f32 v[54:55], v[54:55], v[62:63]
	v_lshlrev_b32_e32 v68, 16, v157
	v_and_b32_e32 v69, 0xffff0000, v157
	v_pk_add_f32 v[64:65], v[50:51], v[66:67]
	v_mul_f32_e32 v50, v55, v55
	v_mul_f32_e32 v51, v57, v57
	v_pk_add_f32 v[62:63], v[52:53], v[68:69]
	v_fmac_f32_e32 v50, v54, v54
	v_fmac_f32_e32 v51, v56, v56
	v_add_f32_e32 v50, v50, v51
	v_mul_f32_e32 v51, v65, v65
	v_mul_f32_e32 v52, v63, v63
	v_fmac_f32_e32 v51, v64, v64
	v_fmac_f32_e32 v52, v62, v62
	v_add_f32_e32 v51, v51, v52
	v_add_f32_e32 v50, v50, v51
	v_add_f32_e32 v53, v70, v50
	v_mov_b32_e32 v68, v53
	s_nop 1
	v_permlane16_swap_b32_e32 v53, v68
	v_lshl_add_u64 v[50:51], s[42:43], 0, v[204:205]
	v_lshl_add_u64 v[66:67], v[196:197], 1, v[50:51]
	global_store_dwordx4 v[66:67], v[58:61], off
	v_cvt_pk_bf16_f32 v52, v54, v55
	s_waitcnt lgkmcnt(0)
	v_add_f32_e32 v50, v53, v68
	v_mov_b32_e32 v51, v50
	s_nop 1
	v_permlane32_swap_b32_e32 v50, v51
	v_cvt_pk_bf16_f32 v53, v56, v57
	v_cvt_pk_bf16_f32 v54, v64, v65
	v_cvt_pk_bf16_f32 v55, v62, v63
	global_store_dwordx4 v[66:67], v[52:55], off offset:256
	s_and_saveexec_b64 s[6:7], vcc
	s_cbranch_execz .LBB0_1497
	s_waitcnt lgkmcnt(0)
	v_add_f32_e32 v50, v50, v51
	v_lshl_add_u32 v51, v225, 4, s15
	ds_write_b32 v51, v50
.LBB0_1497:
	s_or_b64 exec, exec, s[6:7]
	v_lshlrev_b32_e32 v50, 16, v150
	s_waitcnt lgkmcnt(0)
	v_and_b32_e32 v51, 0xffff0000, v150
	v_lshlrev_b32_e32 v52, 16, v151
	v_and_b32_e32 v53, 0xffff0000, v151
	v_lshlrev_b32_e32 v54, 16, v152
	v_and_b32_e32 v55, 0xffff0000, v152
	v_lshlrev_b32_e32 v56, 16, v153
	v_and_b32_e32 v57, 0xffff0000, v153
	v_pk_add_f32 v[48:49], v[48:49], v[52:53]
	v_pk_add_f32 v[46:47], v[46:47], v[50:51]
	v_pk_add_f32 v[50:51], v[44:45], v[56:57]
	v_pk_add_f32 v[44:45], v[42:43], v[54:55]
	v_mul_f32_e32 v42, v47, v47
	v_mul_f32_e32 v43, v49, v49
	v_fmac_f32_e32 v42, v46, v46
	v_fmac_f32_e32 v43, v48, v48
	v_add_f32_e32 v42, v42, v43
	v_mul_f32_e32 v43, v45, v45
	v_mul_f32_e32 v52, v51, v51
	v_fmac_f32_e32 v43, v44, v44
	v_fmac_f32_e32 v52, v50, v50
	v_add_f32_e32 v43, v43, v52
	v_add_f32_e32 v54, v42, v43
	v_cvt_pk_bf16_f32 v42, v46, v47
	v_cvt_pk_bf16_f32 v43, v48, v49
	v_lshlrev_b32_e32 v46, 16, v146
	v_and_b32_e32 v47, 0xffff0000, v146
	v_lshlrev_b32_e32 v48, 16, v147
	v_and_b32_e32 v49, 0xffff0000, v147
	v_cvt_pk_bf16_f32 v44, v44, v45
	v_cvt_pk_bf16_f32 v45, v50, v51
	v_lshlrev_b32_e32 v50, 16, v148
	v_and_b32_e32 v51, 0xffff0000, v148
	v_pk_add_f32 v[40:41], v[40:41], v[48:49]
	v_pk_add_f32 v[38:39], v[38:39], v[46:47]
	v_lshlrev_b32_e32 v52, 16, v149
	v_and_b32_e32 v53, 0xffff0000, v149
	v_pk_add_f32 v[48:49], v[34:35], v[50:51]
	v_mul_f32_e32 v34, v39, v39
	v_mul_f32_e32 v35, v41, v41
	v_pk_add_f32 v[46:47], v[36:37], v[52:53]
	v_fmac_f32_e32 v34, v38, v38
	v_fmac_f32_e32 v35, v40, v40
	v_add_f32_e32 v34, v34, v35
	v_mul_f32_e32 v35, v49, v49
	v_mul_f32_e32 v36, v47, v47
	v_fmac_f32_e32 v35, v48, v48
	v_fmac_f32_e32 v36, v46, v46
	v_add_f32_e32 v35, v35, v36
	v_add_f32_e32 v34, v34, v35
	v_add_f32_e32 v37, v54, v34
	v_mov_b32_e32 v52, v37
	s_nop 1
	v_permlane16_swap_b32_e32 v37, v52
	v_lshl_add_u64 v[34:35], s[42:43], 0, v[202:203]
	v_lshl_add_u64 v[50:51], v[196:197], 1, v[34:35]
	global_store_dwordx4 v[50:51], v[42:45], off
	v_cvt_pk_bf16_f32 v36, v38, v39
	s_waitcnt lgkmcnt(0)
	v_add_f32_e32 v34, v37, v52
	v_mov_b32_e32 v35, v34
	s_nop 1
	v_permlane32_swap_b32_e32 v34, v35
	v_cvt_pk_bf16_f32 v37, v40, v41
	v_cvt_pk_bf16_f32 v38, v48, v49
	v_cvt_pk_bf16_f32 v39, v46, v47
	global_store_dwordx4 v[50:51], v[36:39], off offset:256
	s_and_saveexec_b64 s[6:7], vcc
	s_cbranch_execz .LBB0_1499
	s_waitcnt lgkmcnt(0)
	v_add_f32_e32 v34, v34, v35
	v_lshl_add_u32 v35, v224, 4, s15
	ds_write_b32 v35, v34
.LBB0_1499:
	s_or_b64 exec, exec, s[6:7]
	v_lshlrev_b32_e32 v34, 16, v142
	s_waitcnt lgkmcnt(0)
	v_and_b32_e32 v35, 0xffff0000, v142
	v_lshlrev_b32_e32 v36, 16, v143
	v_and_b32_e32 v37, 0xffff0000, v143
	v_lshlrev_b32_e32 v38, 16, v144
	v_and_b32_e32 v39, 0xffff0000, v144
	v_lshlrev_b32_e32 v40, 16, v145
	v_and_b32_e32 v41, 0xffff0000, v145
	v_pk_add_f32 v[32:33], v[32:33], v[36:37]
	v_pk_add_f32 v[30:31], v[30:31], v[34:35]
	v_pk_add_f32 v[34:35], v[28:29], v[40:41]
	v_pk_add_f32 v[28:29], v[26:27], v[38:39]
	v_mul_f32_e32 v26, v31, v31
	v_mul_f32_e32 v27, v33, v33
	v_fmac_f32_e32 v26, v30, v30
	v_fmac_f32_e32 v27, v32, v32
	v_add_f32_e32 v26, v26, v27
	v_mul_f32_e32 v27, v29, v29
	v_mul_f32_e32 v36, v35, v35
	v_fmac_f32_e32 v27, v28, v28
	v_fmac_f32_e32 v36, v34, v34
	v_add_f32_e32 v27, v27, v36
	v_add_f32_e32 v38, v26, v27
	v_cvt_pk_bf16_f32 v26, v30, v31
	v_cvt_pk_bf16_f32 v27, v32, v33
	v_lshlrev_b32_e32 v30, 16, v138
	v_and_b32_e32 v31, 0xffff0000, v138
	v_lshlrev_b32_e32 v32, 16, v139
	v_and_b32_e32 v33, 0xffff0000, v139
	v_cvt_pk_bf16_f32 v28, v28, v29
	v_cvt_pk_bf16_f32 v29, v34, v35
	v_lshlrev_b32_e32 v34, 16, v140
	v_and_b32_e32 v35, 0xffff0000, v140
	v_pk_add_f32 v[24:25], v[24:25], v[32:33]
	v_pk_add_f32 v[22:23], v[22:23], v[30:31]
	v_lshlrev_b32_e32 v36, 16, v141
	v_and_b32_e32 v37, 0xffff0000, v141
	v_pk_add_f32 v[32:33], v[18:19], v[34:35]
	v_mul_f32_e32 v18, v23, v23
	v_mul_f32_e32 v19, v25, v25
	v_pk_add_f32 v[30:31], v[20:21], v[36:37]
	v_fmac_f32_e32 v18, v22, v22
	v_fmac_f32_e32 v19, v24, v24
	v_add_f32_e32 v18, v18, v19
	v_mul_f32_e32 v19, v33, v33
	v_mul_f32_e32 v20, v31, v31
	v_fmac_f32_e32 v19, v32, v32
	v_fmac_f32_e32 v20, v30, v30
	v_add_f32_e32 v19, v19, v20
	v_add_f32_e32 v18, v18, v19
	v_add_f32_e32 v21, v38, v18
	v_mov_b32_e32 v36, v21
	s_nop 1
	v_permlane16_swap_b32_e32 v21, v36
	v_lshl_add_u64 v[18:19], s[42:43], 0, v[200:201]
	v_lshl_add_u64 v[34:35], v[196:197], 1, v[18:19]
	global_store_dwordx4 v[34:35], v[26:29], off
	v_cvt_pk_bf16_f32 v20, v22, v23
	s_waitcnt lgkmcnt(0)
	v_add_f32_e32 v18, v21, v36
	v_mov_b32_e32 v19, v18
	s_nop 1
	v_permlane32_swap_b32_e32 v18, v19
	v_cvt_pk_bf16_f32 v21, v24, v25
	v_cvt_pk_bf16_f32 v22, v32, v33
	v_cvt_pk_bf16_f32 v23, v30, v31
	global_store_dwordx4 v[34:35], v[20:23], off offset:256
	s_and_saveexec_b64 s[6:7], vcc
	s_cbranch_execz .LBB0_1501
	s_waitcnt lgkmcnt(0)
	v_add_f32_e32 v18, v18, v19
	v_lshl_add_u32 v19, v223, 4, s15
	ds_write_b32 v19, v18
.LBB0_1501:
	s_or_b64 exec, exec, s[6:7]
	v_lshlrev_b32_e32 v18, 16, v134
	s_waitcnt lgkmcnt(0)
	v_and_b32_e32 v19, 0xffff0000, v134
	v_lshlrev_b32_e32 v20, 16, v135
	v_and_b32_e32 v21, 0xffff0000, v135
	v_lshlrev_b32_e32 v22, 16, v136
	v_and_b32_e32 v23, 0xffff0000, v136
	v_lshlrev_b32_e32 v24, 16, v137
	v_and_b32_e32 v25, 0xffff0000, v137
	v_pk_add_f32 v[16:17], v[16:17], v[20:21]
	v_pk_add_f32 v[14:15], v[14:15], v[18:19]
	v_pk_add_f32 v[18:19], v[12:13], v[24:25]
	v_pk_add_f32 v[12:13], v[10:11], v[22:23]
	v_mul_f32_e32 v10, v15, v15
	v_mul_f32_e32 v11, v17, v17
	v_fmac_f32_e32 v10, v14, v14
	v_fmac_f32_e32 v11, v16, v16
	v_add_f32_e32 v10, v10, v11
	v_mul_f32_e32 v11, v13, v13
	v_mul_f32_e32 v20, v19, v19
	v_fmac_f32_e32 v11, v12, v12
	v_fmac_f32_e32 v20, v18, v18
	v_add_f32_e32 v11, v11, v20
	v_add_f32_e32 v22, v10, v11
	v_cvt_pk_bf16_f32 v10, v14, v15
	v_cvt_pk_bf16_f32 v11, v16, v17
	v_lshlrev_b32_e32 v14, 16, v130
	v_and_b32_e32 v15, 0xffff0000, v130
	v_lshlrev_b32_e32 v16, 16, v131
	v_and_b32_e32 v17, 0xffff0000, v131
	v_cvt_pk_bf16_f32 v12, v12, v13
	v_cvt_pk_bf16_f32 v13, v18, v19
	v_lshlrev_b32_e32 v18, 16, v132
	v_and_b32_e32 v19, 0xffff0000, v132
	v_pk_add_f32 v[8:9], v[8:9], v[16:17]
	v_pk_add_f32 v[6:7], v[6:7], v[14:15]
	v_lshlrev_b32_e32 v20, 16, v133
	v_and_b32_e32 v21, 0xffff0000, v133
	v_pk_add_f32 v[16:17], v[2:3], v[18:19]
	v_mul_f32_e32 v2, v7, v7
	v_mul_f32_e32 v3, v9, v9
	v_pk_add_f32 v[14:15], v[4:5], v[20:21]
	v_fmac_f32_e32 v2, v6, v6
	v_fmac_f32_e32 v3, v8, v8
	v_add_f32_e32 v2, v2, v3
	v_mul_f32_e32 v3, v17, v17
	v_mul_f32_e32 v4, v15, v15
	v_fmac_f32_e32 v3, v16, v16
	v_fmac_f32_e32 v4, v14, v14
	v_add_f32_e32 v3, v3, v4
	v_add_f32_e32 v2, v2, v3
	v_add_f32_e32 v5, v22, v2
	v_mov_b32_e32 v20, v5
	s_nop 1
	v_permlane16_swap_b32_e32 v5, v20
	v_lshl_add_u64 v[2:3], s[42:43], 0, v[198:199]
	v_lshl_add_u64 v[18:19], v[196:197], 1, v[2:3]
	global_store_dwordx4 v[18:19], v[10:13], off
	v_cvt_pk_bf16_f32 v4, v6, v7
	s_waitcnt lgkmcnt(0)
	v_add_f32_e32 v2, v5, v20
	v_mov_b32_e32 v3, v2
	s_nop 1
	v_permlane32_swap_b32_e32 v2, v3
	v_cvt_pk_bf16_f32 v5, v8, v9
	v_cvt_pk_bf16_f32 v6, v16, v17
	v_cvt_pk_bf16_f32 v7, v14, v15
	global_store_dwordx4 v[18:19], v[4:7], off offset:256
	s_and_saveexec_b64 s[6:7], vcc
	s_cbranch_execz .LBB0_1503
	s_waitcnt lgkmcnt(0)
	v_add_f32_e32 v2, v2, v3
	v_lshl_add_u32 v3, v222, 4, s15
	ds_write_b32 v3, v2

.LBB0_2145:
	s_or_b64 exec, exec, s[60:61]
	v_mov_b32_e32 v130, v0
	v_readlane_b32 s36, v254, 62
	s_barrier
	s_lshr_b32 s17, s73, 2
	s_and_b32 vcc_lo, s73, 3
	v_readlane_b32 s37, v254, 63
	v_ashrrev_i32_e32 v131, 31, v130
	s_lshl_b32 s33, s17, 4
	v_lshl_add_u64 v[130:131], v[130:131], 4, s[36:37]
	s_lshl_b32 s36, vcc_lo, 1
	s_or_b32 s36, s33, s36
	s_ashr_i32 s59, s58, 31
	s_or_b32 s40, s36, 8
	s_lshl_b64 s[62:63], s[58:59], 17
	s_mov_b32 s37, s41
	s_lshl_b64 s[60:61], s[40:41], 12
	v_lshl_add_u64 v[132:133], v[130:131], 0, s[62:63]
	s_lshl_b64 s[62:63], s[36:37], 12
	s_or_b32 s40, s36, 1
	v_lshl_add_u64 v[134:135], v[132:133], 0, s[62:63]
	s_add_u32 s64, s62, 8
	s_addc_u32 s65, s63, 0
	s_or_b32 s40, s36, 9
	s_or_b32 s36, s58, 1
	global_load_dwordx2 v[154:155], v[134:135], off sc1
	v_lshl_add_u64 v[134:135], v[132:133], 0, s[64:65]
	s_add_u32 s66, s60, 8
	s_addc_u32 s67, s61, 0
	s_ashr_i32 s37, s36, 31
	global_load_dwordx2 v[156:157], v[134:135], off sc1
	v_lshl_add_u64 v[134:135], v[132:133], 0, s[60:61]
	v_lshl_add_u64 v[132:133], v[132:133], 0, s[66:67]
	s_lshl_b64 s[36:37], s[36:37], 17
	global_load_dwordx2 v[158:159], v[134:135], off sc1
	global_load_dwordx2 v[160:161], v[132:133], off sc1
	v_lshl_add_u64 v[132:133], v[130:131], 0, s[36:37]
	v_lshl_add_u64 v[134:135], v[132:133], 0, s[62:63]
	s_or_b32 s36, s58, 2
	global_load_dwordx2 v[162:163], v[134:135], off sc1
	v_lshl_add_u64 v[134:135], v[132:133], 0, s[64:65]
	s_ashr_i32 s37, s36, 31
	global_load_dwordx2 v[164:165], v[134:135], off sc1
	v_lshl_add_u64 v[134:135], v[132:133], 0, s[60:61]
	v_lshl_add_u64 v[132:133], v[132:133], 0, s[66:67]
	s_lshl_b64 s[36:37], s[36:37], 17
	global_load_dwordx2 v[166:167], v[134:135], off sc1
	global_load_dwordx2 v[168:169], v[132:133], off sc1
	v_lshl_add_u64 v[132:133], v[130:131], 0, s[36:37]
	v_lshl_add_u64 v[134:135], v[132:133], 0, s[62:63]
	s_or_b32 s36, s58, 3
	global_load_dwordx2 v[170:171], v[134:135], off sc1
	v_lshl_add_u64 v[134:135], v[132:133], 0, s[64:65]
	s_ashr_i32 s37, s36, 31
	global_load_dwordx2 v[172:173], v[134:135], off sc1
	v_lshl_add_u64 v[134:135], v[132:133], 0, s[60:61]
	v_lshl_add_u64 v[132:133], v[132:133], 0, s[66:67]
	s_lshl_b64 s[36:37], s[36:37], 17
	global_load_dwordx2 v[174:175], v[134:135], off sc1
	global_load_dwordx2 v[176:177], v[132:133], off sc1
	v_lshl_add_u64 v[132:133], v[130:131], 0, s[36:37]
	v_lshl_add_u64 v[134:135], v[132:133], 0, s[62:63]
	s_or_b32 s36, s58, 4
	global_load_dwordx2 v[178:179], v[134:135], off sc1
	v_lshl_add_u64 v[134:135], v[132:133], 0, s[64:65]
	s_ashr_i32 s37, s36, 31
	global_load_dwordx2 v[180:181], v[134:135], off sc1
	v_lshl_add_u64 v[134:135], v[132:133], 0, s[60:61]
	v_lshl_add_u64 v[132:133], v[132:133], 0, s[66:67]
	s_lshl_b64 s[36:37], s[36:37], 17
	global_load_dwordx2 v[182:183], v[134:135], off sc1
	global_load_dwordx2 v[184:185], v[132:133], off sc1
	v_lshl_add_u64 v[132:133], v[130:131], 0, s[36:37]
	v_lshl_add_u64 v[134:135], v[132:133], 0, s[62:63]
	global_load_dwordx2 v[186:187], v[134:135], off sc1
	v_lshl_add_u64 v[134:135], v[132:133], 0, s[64:65]
	global_load_dwordx2 v[188:189], v[134:135], off sc1
	v_lshl_add_u64 v[134:135], v[132:133], 0, s[60:61]
	global_load_dwordx2 v[190:191], v[134:135], off sc1
	v_lshl_add_u64 v[132:133], v[132:133], 0, s[66:67]
	global_load_dwordx2 v[192:193], v[132:133], off sc1
	s_or_b32 s36, s58, 5
	s_ashr_i32 s37, s36, 31
	s_lshl_b64 s[36:37], s[36:37], 17
	v_lshl_add_u64 v[132:133], v[130:131], 0, s[36:37]
	v_lshl_add_u64 v[134:135], v[132:133], 0, s[62:63]
	global_load_dwordx2 v[152:153], v[134:135], off sc1
	v_lshl_add_u64 v[134:135], v[132:133], 0, s[64:65]
	global_load_dwordx2 v[150:151], v[134:135], off sc1
	v_lshl_add_u64 v[134:135], v[132:133], 0, s[60:61]
	global_load_dwordx2 v[148:149], v[134:135], off sc1
	s_or_b32 s36, s58, 6
	s_ashr_i32 s37, s36, 31
	v_lshl_add_u64 v[132:133], v[132:133], 0, s[66:67]
	s_lshl_b64 s[36:37], s[36:37], 17
	global_load_dwordx2 v[144:145], v[132:133], off sc1
	v_lshl_add_u64 v[132:133], v[130:131], 0, s[36:37]
	v_lshl_add_u64 v[134:135], v[132:133], 0, s[62:63]
	s_or_b32 s36, s58, 7
	global_load_dwordx2 v[146:147], v[134:135], off sc1
	v_lshl_add_u64 v[134:135], v[132:133], 0, s[64:65]
	s_ashr_i32 s37, s36, 31
	global_load_dwordx2 v[142:143], v[134:135], off sc1
	v_lshl_add_u64 v[134:135], v[132:133], 0, s[60:61]
	s_lshl_b64 s[36:37], s[36:37], 17
	global_load_dwordx2 v[140:141], v[134:135], off sc1
	v_lshl_add_u64 v[132:133], v[132:133], 0, s[66:67]
	v_lshl_add_u64 v[130:131], v[130:131], 0, s[36:37]
	global_load_dwordx2 v[136:137], v[132:133], off sc1
	v_lshl_add_u64 v[132:133], v[130:131], 0, s[62:63]
	global_load_dwordx2 v[138:139], v[132:133], off sc1
	v_lshl_add_u64 v[132:133], v[130:131], 0, s[64:65]
	global_load_dwordx2 v[134:135], v[132:133], off sc1
	s_waitcnt vmcnt(29)
	v_lshlrev_b32_e32 v200, 16, v154
	v_and_b32_e32 v201, 0xffff0000, v154
	v_lshlrev_b32_e32 v154, 16, v155
	v_and_b32_e32 v155, 0xffff0000, v155
	v_pk_add_f32 v[154:155], v[154:155], 0 op_sel_hi:[1,0]
	s_waitcnt vmcnt(28)
	v_lshlrev_b32_e32 v202, 16, v156
	v_and_b32_e32 v203, 0xffff0000, v156
	v_lshlrev_b32_e32 v156, 16, v157
	v_and_b32_e32 v157, 0xffff0000, v157
	s_waitcnt vmcnt(25)
	v_lshlrev_b32_e32 v208, 16, v162
	v_and_b32_e32 v209, 0xffff0000, v162
	v_lshlrev_b32_e32 v162, 16, v163
	v_and_b32_e32 v163, 0xffff0000, v163
	v_pk_add_f32 v[156:157], v[156:157], 0 op_sel_hi:[1,0]
	v_lshlrev_b32_e32 v204, 16, v158
	v_and_b32_e32 v205, 0xffff0000, v158
	v_lshlrev_b32_e32 v158, 16, v159
	v_and_b32_e32 v159, 0xffff0000, v159
	v_pk_add_f32 v[154:155], v[154:155], v[162:163]
	s_waitcnt vmcnt(24)
	v_lshlrev_b32_e32 v162, 16, v164
	v_and_b32_e32 v163, 0xffff0000, v164
	v_lshlrev_b32_e32 v164, 16, v165
	v_and_b32_e32 v165, 0xffff0000, v165
	v_pk_add_f32 v[158:159], v[158:159], 0 op_sel_hi:[1,0]
	v_lshlrev_b32_e32 v206, 16, v160
	v_and_b32_e32 v207, 0xffff0000, v160
	v_lshlrev_b32_e32 v160, 16, v161
	v_and_b32_e32 v161, 0xffff0000, v161
	v_pk_add_f32 v[156:157], v[156:157], v[164:165]
	s_waitcnt vmcnt(23)
	v_lshlrev_b32_e32 v164, 16, v166
	v_and_b32_e32 v165, 0xffff0000, v166
	v_lshlrev_b32_e32 v166, 16, v167
	v_and_b32_e32 v167, 0xffff0000, v167
	v_pk_add_f32 v[160:161], v[160:161], 0 op_sel_hi:[1,0]
	v_pk_add_f32 v[158:159], v[158:159], v[166:167]
	s_waitcnt vmcnt(22)
	v_lshlrev_b32_e32 v166, 16, v168
	v_and_b32_e32 v167, 0xffff0000, v168
	v_lshlrev_b32_e32 v168, 16, v169
	v_and_b32_e32 v169, 0xffff0000, v169
	v_pk_add_f32 v[160:161], v[160:161], v[168:169]
	s_waitcnt vmcnt(21)
	v_lshlrev_b32_e32 v168, 16, v170
	v_and_b32_e32 v169, 0xffff0000, v170
	v_lshlrev_b32_e32 v170, 16, v171
	v_and_b32_e32 v171, 0xffff0000, v171
	v_pk_add_f32 v[154:155], v[154:155], v[170:171]
	s_waitcnt vmcnt(20)
	v_lshlrev_b32_e32 v170, 16, v172
	v_and_b32_e32 v171, 0xffff0000, v172
	v_lshlrev_b32_e32 v172, 16, v173
	v_and_b32_e32 v173, 0xffff0000, v173
	v_pk_add_f32 v[156:157], v[156:157], v[172:173]
	s_waitcnt vmcnt(19)
	v_lshlrev_b32_e32 v172, 16, v175
	v_and_b32_e32 v173, 0xffff0000, v175
	v_pk_add_f32 v[202:203], v[202:203], 0 op_sel_hi:[1,0]
	v_pk_add_f32 v[158:159], v[158:159], v[172:173]
	s_waitcnt vmcnt(18)
	v_lshlrev_b32_e32 v172, 16, v177
	v_and_b32_e32 v173, 0xffff0000, v177
	v_pk_add_f32 v[204:205], v[204:205], 0 op_sel_hi:[1,0]
	v_pk_add_f32 v[162:163], v[202:203], v[162:163]
	v_pk_add_f32 v[160:161], v[160:161], v[172:173]
	s_waitcnt vmcnt(17)
	v_lshlrev_b32_e32 v172, 16, v179
	v_and_b32_e32 v173, 0xffff0000, v179
	v_pk_add_f32 v[200:201], v[200:201], 0 op_sel_hi:[1,0]
	v_pk_add_f32 v[206:207], v[206:207], 0 op_sel_hi:[1,0]
	v_pk_add_f32 v[164:165], v[204:205], v[164:165]
	v_pk_add_f32 v[162:163], v[162:163], v[170:171]
	v_lshlrev_b32_e32 v170, 16, v174
	v_and_b32_e32 v171, 0xffff0000, v174
	v_pk_add_f32 v[154:155], v[154:155], v[172:173]
	s_waitcnt vmcnt(16)
	v_lshlrev_b32_e32 v172, 16, v181
	v_and_b32_e32 v173, 0xffff0000, v181
	v_pk_add_f32 v[200:201], v[200:201], v[208:209]
	v_pk_add_f32 v[166:167], v[206:207], v[166:167]
	v_pk_add_f32 v[164:165], v[164:165], v[170:171]
	v_lshlrev_b32_e32 v170, 16, v176
	v_and_b32_e32 v171, 0xffff0000, v176
	v_pk_add_f32 v[156:157], v[156:157], v[172:173]
	s_waitcnt vmcnt(15)
	v_lshlrev_b32_e32 v172, 16, v183
	v_and_b32_e32 v173, 0xffff0000, v183
	v_pk_add_f32 v[168:169], v[200:201], v[168:169]
	v_pk_add_f32 v[166:167], v[166:167], v[170:171]
	v_lshlrev_b32_e32 v170, 16, v178
	v_and_b32_e32 v171, 0xffff0000, v178
	v_pk_add_f32 v[158:159], v[158:159], v[172:173]
	s_waitcnt vmcnt(14)
	v_lshlrev_b32_e32 v172, 16, v185
	v_and_b32_e32 v173, 0xffff0000, v185
	v_pk_add_f32 v[168:169], v[168:169], v[170:171]
	v_lshlrev_b32_e32 v170, 16, v180
	v_and_b32_e32 v171, 0xffff0000, v180
	v_pk_add_f32 v[160:161], v[160:161], v[172:173]
	s_waitcnt vmcnt(13)
	v_lshlrev_b32_e32 v172, 16, v187
	v_and_b32_e32 v173, 0xffff0000, v187
	v_pk_add_f32 v[162:163], v[162:163], v[170:171]
	v_lshlrev_b32_e32 v170, 16, v182
	v_and_b32_e32 v171, 0xffff0000, v182
	v_pk_add_f32 v[172:173], v[154:155], v[172:173]
	s_waitcnt vmcnt(12)
	v_lshlrev_b32_e32 v154, 16, v188
	v_and_b32_e32 v155, 0xffff0000, v188
	v_pk_add_f32 v[164:165], v[164:165], v[170:171]
	v_pk_add_f32 v[174:175], v[162:163], v[154:155]
	s_waitcnt vmcnt(11)
	v_lshlrev_b32_e32 v154, 16, v190
	v_and_b32_e32 v155, 0xffff0000, v190
	v_pk_add_f32 v[164:165], v[164:165], v[154:155]
	s_waitcnt vmcnt(10)
	v_lshlrev_b32_e32 v154, 16, v193
	v_and_b32_e32 v155, 0xffff0000, v193
	s_lshl_b32 s33, s72, 8
	v_lshl_add_u32 v162, s17, 7, v217
	v_pk_add_f32 v[160:161], v[160:161], v[154:155]
	s_lshl_b32 s36, vcc_lo, 4
	v_add_u32_e32 v154, s33, v162
	v_or_b32_e32 v154, s36, v154
	v_lshlrev_b32_e32 v170, 16, v184
	v_and_b32_e32 v171, 0xffff0000, v184
	v_ashrrev_i32_e32 v155, 31, v154
	v_lshl_add_u64 v[132:133], v[130:131], 0, s[60:61]
	v_pk_add_f32 v[166:167], v[166:167], v[170:171]
	v_lshlrev_b32_e32 v170, 16, v186
	v_and_b32_e32 v171, 0xffff0000, v186
	v_lshl_or_b32 v200, s16, 8, v222
	v_lshlrev_b64 v[154:155], 11, v[154:155]
	global_load_dwordx2 v[132:133], v[132:133], off sc1
	v_lshl_add_u64 v[130:131], v[130:131], 0, s[66:67]
	v_pk_add_f32 v[168:169], v[168:169], v[170:171]
	v_lshlrev_b32_e32 v170, 16, v189
	v_and_b32_e32 v171, 0xffff0000, v189
	v_ashrrev_i32_e32 v201, 31, v200
	v_lshl_add_u64 v[154:155], s[42:43], 0, v[154:155]
	global_load_dwordx2 v[130:131], v[130:131], off sc1
	v_pk_add_f32 v[170:171], v[156:157], v[170:171]
	v_lshlrev_b32_e32 v156, 16, v191
	v_and_b32_e32 v157, 0xffff0000, v191
	v_lshl_add_u64 v[178:179], v[200:201], 1, v[154:155]
	v_pk_add_f32 v[158:159], v[158:159], v[156:157]
	global_load_dwordx4 v[154:157], v[178:179], off
	v_lshlrev_b32_e32 v176, 16, v192
	v_and_b32_e32 v177, 0xffff0000, v192
	v_pk_add_f32 v[176:177], v[166:167], v[176:177]
	s_waitcnt vmcnt(12)
	v_lshlrev_b32_e32 v166, 16, v152
	v_and_b32_e32 v167, 0xffff0000, v152
	v_lshlrev_b32_e32 v152, 16, v153
	v_and_b32_e32 v153, 0xffff0000, v153
	v_pk_add_f32 v[168:169], v[168:169], v[166:167]
	s_waitcnt vmcnt(11)
	v_lshlrev_b32_e32 v166, 16, v150
	v_and_b32_e32 v167, 0xffff0000, v150
	v_pk_add_f32 v[152:153], v[172:173], v[152:153]
	v_lshlrev_b32_e32 v150, 16, v151
	v_and_b32_e32 v151, 0xffff0000, v151
	v_pk_add_f32 v[172:173], v[174:175], v[166:167]
	s_waitcnt vmcnt(10)
	v_lshlrev_b32_e32 v166, 16, v148
	v_and_b32_e32 v167, 0xffff0000, v148
	v_pk_add_f32 v[150:151], v[170:171], v[150:151]
	v_pk_add_f32 v[170:171], v[164:165], v[166:167]
	global_load_dwordx4 v[164:167], v[178:179], off offset:256
	v_lshlrev_b32_e32 v148, 16, v149
	v_and_b32_e32 v149, 0xffff0000, v149
	v_pk_add_f32 v[148:149], v[158:159], v[148:149]
	s_waitcnt vmcnt(10)
	v_lshlrev_b32_e32 v158, 16, v144
	v_and_b32_e32 v159, 0xffff0000, v144
	v_lshlrev_b32_e32 v144, 16, v145
	v_and_b32_e32 v145, 0xffff0000, v145
	v_pk_add_f32 v[144:145], v[160:161], v[144:145]
	s_waitcnt vmcnt(9)
	v_lshlrev_b32_e32 v160, 16, v146
	v_and_b32_e32 v161, 0xffff0000, v146
	v_lshlrev_b32_e32 v146, 16, v147
	v_and_b32_e32 v147, 0xffff0000, v147
	v_pk_add_f32 v[146:147], v[152:153], v[146:147]
	v_pk_add_f32 v[152:153], v[168:169], v[160:161]
	s_waitcnt vmcnt(8)
	v_lshlrev_b32_e32 v160, 16, v142
	v_and_b32_e32 v161, 0xffff0000, v142
	v_lshlrev_b32_e32 v142, 16, v143
	v_and_b32_e32 v143, 0xffff0000, v143
	v_pk_add_f32 v[142:143], v[150:151], v[142:143]
	v_pk_add_f32 v[150:151], v[172:173], v[160:161]
	s_waitcnt vmcnt(7)
	v_lshlrev_b32_e32 v160, 16, v140
	v_and_b32_e32 v161, 0xffff0000, v140
	v_lshlrev_b32_e32 v140, 16, v141
	v_and_b32_e32 v141, 0xffff0000, v141
	v_pk_add_f32 v[158:159], v[176:177], v[158:159]
	v_pk_add_f32 v[148:149], v[148:149], v[140:141]
	s_waitcnt vmcnt(6)
	v_lshlrev_b32_e32 v140, 16, v136
	v_and_b32_e32 v141, 0xffff0000, v136
	v_pk_add_f32 v[168:169], v[170:171], v[160:161]
	v_pk_add_f32 v[170:171], v[158:159], v[140:141]
	s_waitcnt vmcnt(5)
	v_lshlrev_b32_e32 v140, 16, v138
	v_and_b32_e32 v141, 0xffff0000, v138
	v_lshlrev_b32_e32 v138, 16, v139
	v_and_b32_e32 v139, 0xffff0000, v139
	v_readlane_b32 s60, v254, 0
	v_pk_add_f32 v[146:147], v[146:147], v[138:139]
	s_waitcnt vmcnt(4)
	v_lshlrev_b32_e32 v138, 16, v134
	v_and_b32_e32 v139, 0xffff0000, v134
	v_lshlrev_b32_e32 v134, 16, v135
	v_and_b32_e32 v135, 0xffff0000, v135
	v_readlane_b32 s66, v254, 6
	v_readlane_b32 s67, v254, 7
	v_lshlrev_b32_e32 v136, 16, v137
	v_and_b32_e32 v137, 0xffff0000, v137
	v_pk_add_f32 v[134:135], v[142:143], v[134:135]
	v_lshl_add_u64 v[142:143], v[200:201], 2, s[66:67]
	v_pk_add_f32 v[136:137], v[144:145], v[136:137]
	v_pk_add_f32 v[172:173], v[152:153], v[140:141]
	v_pk_add_f32 v[174:175], v[150:151], v[138:139]
	global_load_dwordx4 v[150:153], v[142:143], off offset:16
	global_load_dwordx4 v[158:161], v[142:143], off
	global_load_dwordx4 v[138:141], v[142:143], off offset:528
	s_nop 0
	global_load_dwordx4 v[142:145], v[142:143], off offset:512
	s_waitcnt vmcnt(7)
	v_lshlrev_b32_e32 v176, 16, v132
	v_and_b32_e32 v177, 0xffff0000, v132
	v_lshlrev_b32_e32 v132, 16, v133
	v_and_b32_e32 v133, 0xffff0000, v133
	v_pk_add_f32 v[148:149], v[148:149], v[132:133]
	s_waitcnt vmcnt(6)
	v_lshlrev_b32_e32 v132, 16, v130
	v_and_b32_e32 v133, 0xffff0000, v130
	v_lshlrev_b32_e32 v130, 16, v131
	v_and_b32_e32 v131, 0xffff0000, v131
	v_pk_add_f32 v[168:169], v[168:169], v[176:177]
	v_pk_add_f32 v[170:171], v[170:171], v[132:133]
	v_pk_add_f32 v[176:177], v[136:137], v[130:131]
	s_waitcnt vmcnt(5)
	v_lshlrev_b32_e32 v130, 16, v154
	v_and_b32_e32 v131, 0xffff0000, v154
	v_lshlrev_b32_e32 v132, 16, v155
	v_and_b32_e32 v133, 0xffff0000, v155
	v_pk_fma_f32 v[132:133], v[146:147], 0.5, v[132:133] op_sel_hi:[1,0,1]
	v_pk_fma_f32 v[130:131], v[172:173], 0.5, v[130:131] op_sel_hi:[1,0,1]
	v_mul_f32_e32 v137, v133, v133
	v_mul_f32_e32 v136, v131, v131
	v_fmac_f32_e32 v136, v130, v130
	v_fmac_f32_e32 v137, v132, v132
	v_add_f32_e32 v154, v136, v137
	v_lshlrev_b32_e32 v146, 16, v156
	v_and_b32_e32 v147, 0xffff0000, v156
	v_lshlrev_b32_e32 v136, 16, v157
	v_and_b32_e32 v137, 0xffff0000, v157
	v_pk_fma_f32 v[136:137], v[134:135], 0.5, v[136:137] op_sel_hi:[1,0,1]
	v_pk_fma_f32 v[134:135], v[174:175], 0.5, v[146:147] op_sel_hi:[1,0,1]
	v_mul_f32_e32 v147, v137, v137
	v_mul_f32_e32 v146, v135, v135
	v_fmac_f32_e32 v146, v134, v134
	v_fmac_f32_e32 v147, v136, v136
	v_add_f32_e32 v146, v146, v147
	v_add_f32_e32 v156, v154, v146
	s_waitcnt vmcnt(4)
	v_lshlrev_b32_e32 v146, 16, v164
	v_and_b32_e32 v147, 0xffff0000, v164
	v_lshlrev_b32_e32 v154, 16, v165
	v_and_b32_e32 v155, 0xffff0000, v165
	v_pk_fma_f32 v[148:149], v[148:149], 0.5, v[154:155] op_sel_hi:[1,0,1]
	v_pk_fma_f32 v[146:147], v[168:169], 0.5, v[146:147] op_sel_hi:[1,0,1]
	v_mul_f32_e32 v155, v149, v149
	v_mul_f32_e32 v154, v147, v147
	v_fmac_f32_e32 v154, v146, v146
	v_fmac_f32_e32 v155, v148, v148
	v_add_f32_e32 v154, v154, v155
	v_add_f32_e32 v163, v156, v154
	v_lshlrev_b32_e32 v154, 16, v166
	v_and_b32_e32 v155, 0xffff0000, v166
	v_lshlrev_b32_e32 v156, 16, v167
	v_and_b32_e32 v157, 0xffff0000, v167
	v_pk_fma_f32 v[156:157], v[176:177], 0.5, v[156:157] op_sel_hi:[1,0,1]
	v_pk_fma_f32 v[154:155], v[170:171], 0.5, v[154:155] op_sel_hi:[1,0,1]
	v_mul_f32_e32 v165, v157, v157
	v_mul_f32_e32 v164, v155, v155
	v_fmac_f32_e32 v164, v154, v154
	v_fmac_f32_e32 v165, v156, v156
	v_add_f32_e32 v164, v164, v165
	v_and_b32_e32 v165, 64, v227
	v_add_f32_e32 v163, v163, v164
	v_xor_b32_e32 v164, 16, v227
	v_add_u32_e32 v165, 64, v165
	v_cmp_lt_i32_e32 vcc, v164, v165
	v_readlane_b32 s61, v254, 1
	v_readlane_b32 s62, v254, 2
	v_cndmask_b32_e32 v164, v227, v164, vcc
	v_lshlrev_b32_e32 v164, 2, v164
	v_mov_b32_e32 v164, v163
	s_nop 1
	v_permlane16_swap_b32_e32 v163, v164
	v_readlane_b32 s63, v254, 3
	v_readlane_b32 s64, v254, 4
	v_readlane_b32 s65, v254, 5
	s_waitcnt lgkmcnt(0)
	v_add_f32_e32 v163, v163, v164
	v_xor_b32_e32 v164, 32, v227
	v_cmp_lt_i32_e32 vcc, v164, v165
	s_nop 1
	v_cndmask_b32_e32 v164, v227, v164, vcc
	v_lshlrev_b32_e32 v164, 2, v164
	v_mov_b32_e32 v165, v163
	s_nop 1
	v_permlane32_swap_b32_e32 v163, v165
	v_or_b32_e32 v164, s36, v162
	s_and_saveexec_b64 s[58:59], s[10:11]
	s_cbranch_execz .LBB0_2147
	v_or_b32_e32 v162, s36, v162
	v_lshl_add_u32 v162, v162, 4, s93
	s_waitcnt lgkmcnt(0)
	v_add_f32_e32 v163, v163, v165
	ds_write_b32 v162, v163

.LBB0_2164:
	v_mov_b32_e32 v130, v1
	v_mov_b32_e32 v231, v216
	s_lshl_b32 s17, s16, 8
	s_lshl_b32 s40, s72, 8
	v_add_u32_e32 v228, s88, v130
	s_or_b32 s17, s17, s89
	v_add_u32_e32 v214, s40, v228
	v_lshl_add_u32 v200, v231, 3, s17
	v_ashrrev_i32_e32 v201, 31, v200
	v_ashrrev_i32_e32 v215, 31, v214
	s_waitcnt vmcnt(0)
	v_lshl_add_u64 v[138:139], v[200:201], 1, s[42:43]
	v_lshlrev_b64 v[130:131], 11, v[214:215]
	v_lshl_add_u64 v[130:131], v[138:139], 0, v[130:131]
	global_load_dwordx4 v[190:193], v[130:131], off
	global_load_dwordx4 v[186:189], v[130:131], off offset:256
	v_add_u32_e32 v212, 16, v214
	v_ashrrev_i32_e32 v213, 31, v212
	v_lshlrev_b64 v[130:131], 11, v[212:213]
	v_add_u32_e32 v210, 32, v214
	v_lshl_add_u64 v[130:131], v[138:139], 0, v[130:131]
	v_ashrrev_i32_e32 v211, 31, v210
	global_load_dwordx4 v[182:185], v[130:131], off
	global_load_dwordx4 v[178:181], v[130:131], off offset:256
	v_lshlrev_b64 v[130:131], 11, v[210:211]
	v_add_u32_e32 v208, 48, v214
	v_lshl_add_u64 v[130:131], v[138:139], 0, v[130:131]
	v_ashrrev_i32_e32 v209, 31, v208
	global_load_dwordx4 v[174:177], v[130:131], off
	global_load_dwordx4 v[170:173], v[130:131], off offset:256
	v_lshlrev_b64 v[130:131], 11, v[208:209]
	v_add_u32_e32 v206, 0x80, v214
	v_lshl_add_u64 v[130:131], v[138:139], 0, v[130:131]
	v_ashrrev_i32_e32 v207, 31, v206
	global_load_dwordx4 v[166:169], v[130:131], off
	s_waitcnt lgkmcnt(0)
	global_load_dwordx4 v[162:165], v[130:131], off offset:256
	v_lshlrev_b64 v[130:131], 11, v[206:207]
	v_add_u32_e32 v204, 0x90, v214
	v_lshl_add_u64 v[130:131], v[138:139], 0, v[130:131]
	v_ashrrev_i32_e32 v205, 31, v204
	global_load_dwordx4 v[158:161], v[130:131], off
	global_load_dwordx4 v[154:157], v[130:131], off offset:256
	v_lshlrev_b64 v[130:131], 11, v[204:205]
	v_add_u32_e32 v202, 0xa0, v214
	v_add_u32_e32 v140, 0xb0, v214
	v_lshl_add_u64 v[130:131], v[138:139], 0, v[130:131]
	v_ashrrev_i32_e32 v203, 31, v202
	v_ashrrev_i32_e32 v141, 31, v140
	global_load_dwordx4 v[150:153], v[130:131], off
	global_load_dwordx4 v[142:145], v[130:131], off offset:256
	v_lshlrev_b64 v[130:131], 11, v[202:203]
	v_lshlrev_b64 v[140:141], 11, v[140:141]
	v_lshl_add_u64 v[130:131], v[138:139], 0, v[130:131]
	v_lshl_add_u64 v[138:139], v[138:139], 0, v[140:141]
	global_load_dwordx4 v[134:137], v[130:131], off
	s_nop 0
	global_load_dwordx4 v[130:133], v[130:131], off offset:256
	s_nop 0
	global_load_dwordx4 v[146:149], v[138:139], off
	s_nop 0
	global_load_dwordx4 v[138:141], v[138:139], off offset:256
	v_and_b32_e32 v230, 64, v227
	v_xor_b32_e32 v229, 16, v227
	v_add_u32_e32 v230, 64, v230
	v_cmp_lt_i32_e32 vcc, v229, v230
	v_xor_b32_e32 v232, 32, v227
	s_waitcnt vmcnt(15)
	v_and_b32_e32 v233, 0xffff0000, v190
	v_cndmask_b32_e32 v229, v227, v229, vcc
	v_cmp_lt_i32_e32 vcc, v232, v230
	v_lshlrev_b32_e32 v229, 2, v229
	s_nop 0
	v_cndmask_b32_e32 v230, v227, v232, vcc
	v_lshlrev_b32_e32 v232, 16, v190
	v_lshlrev_b32_e32 v190, 16, v191
	v_and_b32_e32 v191, 0xffff0000, v191
	v_pk_fma_f32 v[128:129], v[128:129], 0.5, v[190:191] op_sel_hi:[1,0,1]
	v_pk_fma_f32 v[126:127], v[126:127], 0.5, v[232:233] op_sel_hi:[1,0,1]
	v_mul_f32_e32 v191, v129, v129
	v_mul_f32_e32 v190, v127, v127
	v_fmac_f32_e32 v190, v126, v126
	v_fmac_f32_e32 v191, v128, v128
	v_cmp_eq_u32_e32 vcc, 0, v231
	v_add_f32_e32 v231, v190, v191
	v_lshlrev_b32_e32 v190, 16, v192
	v_and_b32_e32 v191, 0xffff0000, v192
	v_lshlrev_b32_e32 v192, 16, v193
	v_and_b32_e32 v193, 0xffff0000, v193
	v_pk_fma_f32 v[124:125], v[124:125], 0.5, v[192:193] op_sel_hi:[1,0,1]
	v_pk_fma_f32 v[122:123], v[122:123], 0.5, v[190:191] op_sel_hi:[1,0,1]
	v_mul_f32_e32 v191, v125, v125
	v_mul_f32_e32 v190, v123, v123
	v_fmac_f32_e32 v190, v122, v122
	v_fmac_f32_e32 v191, v124, v124
	v_add_f32_e32 v190, v190, v191
	v_add_f32_e32 v192, v231, v190
	s_waitcnt vmcnt(14)
	v_lshlrev_b32_e32 v190, 16, v186
	v_and_b32_e32 v191, 0xffff0000, v186
	v_lshlrev_b32_e32 v186, 16, v187
	v_and_b32_e32 v187, 0xffff0000, v187
	v_pk_fma_f32 v[120:121], v[120:121], 0.5, v[186:187] op_sel_hi:[1,0,1]
	v_pk_fma_f32 v[118:119], v[118:119], 0.5, v[190:191] op_sel_hi:[1,0,1]
	v_mul_f32_e32 v187, v121, v121
	v_mul_f32_e32 v186, v119, v119
	v_fmac_f32_e32 v186, v118, v118
	v_fmac_f32_e32 v187, v120, v120
	v_add_f32_e32 v186, v186, v187
	v_add_f32_e32 v190, v192, v186
	v_lshlrev_b32_e32 v186, 16, v188
	v_and_b32_e32 v187, 0xffff0000, v188
	v_lshlrev_b32_e32 v188, 16, v189
	v_and_b32_e32 v189, 0xffff0000, v189
	v_pk_fma_f32 v[116:117], v[116:117], 0.5, v[188:189] op_sel_hi:[1,0,1]
	v_pk_fma_f32 v[114:115], v[114:115], 0.5, v[186:187] op_sel_hi:[1,0,1]
	v_mul_f32_e32 v187, v117, v117
	v_mul_f32_e32 v186, v115, v115
	v_fmac_f32_e32 v186, v114, v114
	v_fmac_f32_e32 v187, v116, v116
	v_add_f32_e32 v186, v186, v187
	v_add_f32_e32 v186, v186, v190
	v_mov_b32_e32 v187, v186
	s_nop 1
	v_permlane16_swap_b32_e32 v186, v187
	v_lshlrev_b32_e32 v230, 2, v230
	s_waitcnt lgkmcnt(0)
	v_add_f32_e32 v187, v186, v187
	v_mov_b32_e32 v188, v187
	s_nop 1
	v_permlane32_swap_b32_e32 v187, v188
	v_lshl_add_u32 v186, v228, 4, s93
	s_and_saveexec_b64 s[58:59], vcc
	s_cbranch_execz .LBB0_2166
	s_waitcnt lgkmcnt(0)
	v_add_f32_e32 v187, v187, v188
	ds_write_b32 v186, v187
.LBB0_2166:
	s_or_b64 exec, exec, s[58:59]
	s_waitcnt vmcnt(13) lgkmcnt(0)
	v_lshlrev_b32_e32 v188, 16, v182
	v_and_b32_e32 v189, 0xffff0000, v182
	v_lshlrev_b32_e32 v182, 16, v183
	v_and_b32_e32 v183, 0xffff0000, v183
	v_pk_fma_f32 v[112:113], v[112:113], 0.5, v[182:183] op_sel_hi:[1,0,1]
	v_pk_fma_f32 v[110:111], v[110:111], 0.5, v[188:189] op_sel_hi:[1,0,1]
	v_mul_f32_e32 v183, v113, v113
	v_mul_f32_e32 v182, v111, v111
	v_fmac_f32_e32 v182, v110, v110
	v_fmac_f32_e32 v183, v112, v112
	v_add_f32_e32 v187, v182, v183
	v_lshlrev_b32_e32 v182, 16, v184
	v_and_b32_e32 v183, 0xffff0000, v184
	v_lshlrev_b32_e32 v184, 16, v185
	v_and_b32_e32 v185, 0xffff0000, v185
	v_pk_fma_f32 v[108:109], v[108:109], 0.5, v[184:185] op_sel_hi:[1,0,1]
	v_pk_fma_f32 v[106:107], v[106:107], 0.5, v[182:183] op_sel_hi:[1,0,1]
	v_mul_f32_e32 v183, v109, v109
	v_mul_f32_e32 v182, v107, v107
	v_fmac_f32_e32 v182, v106, v106
	v_fmac_f32_e32 v183, v108, v108
	v_add_f32_e32 v182, v182, v183
	v_add_f32_e32 v184, v187, v182
	s_waitcnt vmcnt(12)
	v_lshlrev_b32_e32 v182, 16, v178
	v_and_b32_e32 v183, 0xffff0000, v178
	v_lshlrev_b32_e32 v178, 16, v179
	v_and_b32_e32 v179, 0xffff0000, v179
	v_pk_fma_f32 v[104:105], v[104:105], 0.5, v[178:179] op_sel_hi:[1,0,1]
	v_pk_fma_f32 v[102:103], v[102:103], 0.5, v[182:183] op_sel_hi:[1,0,1]
	v_mul_f32_e32 v179, v105, v105
	v_mul_f32_e32 v178, v103, v103
	v_fmac_f32_e32 v178, v102, v102
	v_fmac_f32_e32 v179, v104, v104
	v_add_f32_e32 v178, v178, v179
	v_add_f32_e32 v182, v184, v178
	v_lshlrev_b32_e32 v178, 16, v180
	v_and_b32_e32 v179, 0xffff0000, v180
	v_lshlrev_b32_e32 v180, 16, v181
	v_and_b32_e32 v181, 0xffff0000, v181
	v_pk_fma_f32 v[100:101], v[100:101], 0.5, v[180:181] op_sel_hi:[1,0,1]
	v_pk_fma_f32 v[98:99], v[98:99], 0.5, v[178:179] op_sel_hi:[1,0,1]
	v_mul_f32_e32 v179, v101, v101
	v_mul_f32_e32 v178, v99, v99
	v_fmac_f32_e32 v178, v98, v98
	v_fmac_f32_e32 v179, v100, v100
	v_add_f32_e32 v178, v178, v179
	v_add_f32_e32 v178, v178, v182
	v_mov_b32_e32 v179, v178
	s_nop 1
	v_permlane16_swap_b32_e32 v178, v179
	s_waitcnt lgkmcnt(0)
	v_add_f32_e32 v178, v178, v179
	v_mov_b32_e32 v179, v178
	s_nop 1
	v_permlane32_swap_b32_e32 v178, v179
	s_and_saveexec_b64 s[58:59], vcc
	s_cbranch_execz .LBB0_2168
	s_waitcnt lgkmcnt(0)
	v_add_f32_e32 v178, v178, v179
	ds_write_b32 v186, v178 offset:256
.LBB0_2168:
	s_or_b64 exec, exec, s[58:59]
	s_waitcnt vmcnt(11)
	v_lshlrev_b32_e32 v178, 16, v174
	s_waitcnt lgkmcnt(0)
	v_and_b32_e32 v179, 0xffff0000, v174
	v_lshlrev_b32_e32 v174, 16, v175
	v_and_b32_e32 v175, 0xffff0000, v175
	v_pk_fma_f32 v[96:97], v[96:97], 0.5, v[174:175] op_sel_hi:[1,0,1]
	v_pk_fma_f32 v[94:95], v[94:95], 0.5, v[178:179] op_sel_hi:[1,0,1]
	v_mul_f32_e32 v175, v97, v97
	v_mul_f32_e32 v174, v95, v95
	v_fmac_f32_e32 v174, v94, v94
	v_fmac_f32_e32 v175, v96, v96
	v_add_f32_e32 v178, v174, v175
	v_lshlrev_b32_e32 v174, 16, v176
	v_and_b32_e32 v175, 0xffff0000, v176
	v_lshlrev_b32_e32 v176, 16, v177
	v_and_b32_e32 v177, 0xffff0000, v177
	v_pk_fma_f32 v[92:93], v[92:93], 0.5, v[176:177] op_sel_hi:[1,0,1]
	v_pk_fma_f32 v[90:91], v[90:91], 0.5, v[174:175] op_sel_hi:[1,0,1]
	v_mul_f32_e32 v175, v93, v93
	v_mul_f32_e32 v174, v91, v91
	v_fmac_f32_e32 v174, v90, v90
	v_fmac_f32_e32 v175, v92, v92
	v_add_f32_e32 v174, v174, v175
	v_add_f32_e32 v176, v178, v174
	s_waitcnt vmcnt(10)
	v_lshlrev_b32_e32 v174, 16, v170
	v_and_b32_e32 v175, 0xffff0000, v170
	v_lshlrev_b32_e32 v170, 16, v171
	v_and_b32_e32 v171, 0xffff0000, v171
	v_pk_fma_f32 v[88:89], v[88:89], 0.5, v[170:171] op_sel_hi:[1,0,1]
	v_pk_fma_f32 v[86:87], v[86:87], 0.5, v[174:175] op_sel_hi:[1,0,1]
	v_mul_f32_e32 v171, v89, v89
	v_mul_f32_e32 v170, v87, v87
	v_fmac_f32_e32 v170, v86, v86
	v_fmac_f32_e32 v171, v88, v88
	v_add_f32_e32 v170, v170, v171
	v_add_f32_e32 v174, v176, v170
	v_lshlrev_b32_e32 v170, 16, v172
	v_and_b32_e32 v171, 0xffff0000, v172
	v_lshlrev_b32_e32 v172, 16, v173
	v_and_b32_e32 v173, 0xffff0000, v173
	v_pk_fma_f32 v[84:85], v[84:85], 0.5, v[172:173] op_sel_hi:[1,0,1]
	v_pk_fma_f32 v[82:83], v[82:83], 0.5, v[170:171] op_sel_hi:[1,0,1]
	v_mul_f32_e32 v171, v85, v85
	v_mul_f32_e32 v170, v83, v83
	v_fmac_f32_e32 v170, v82, v82
	v_fmac_f32_e32 v171, v84, v84
	v_add_f32_e32 v170, v170, v171
	v_add_f32_e32 v170, v170, v174
	v_mov_b32_e32 v171, v170
	s_nop 1
	v_permlane16_swap_b32_e32 v170, v171
	s_waitcnt lgkmcnt(0)
	v_add_f32_e32 v170, v170, v171
	v_mov_b32_e32 v171, v170
	s_nop 1
	v_permlane32_swap_b32_e32 v170, v171
	s_and_saveexec_b64 s[58:59], vcc
	s_cbranch_execz .LBB0_2170
	s_waitcnt lgkmcnt(0)
	v_add_f32_e32 v170, v170, v171
	ds_write_b32 v186, v170 offset:512
.LBB0_2170:
	s_or_b64 exec, exec, s[58:59]
	s_waitcnt vmcnt(9)
	v_lshlrev_b32_e32 v170, 16, v166
	s_waitcnt lgkmcnt(0)
	v_and_b32_e32 v171, 0xffff0000, v166
	v_lshlrev_b32_e32 v166, 16, v167
	v_and_b32_e32 v167, 0xffff0000, v167
	v_pk_fma_f32 v[80:81], v[80:81], 0.5, v[166:167] op_sel_hi:[1,0,1]
	v_pk_fma_f32 v[78:79], v[78:79], 0.5, v[170:171] op_sel_hi:[1,0,1]
	v_mul_f32_e32 v167, v81, v81
	v_mul_f32_e32 v166, v79, v79
	v_fmac_f32_e32 v166, v78, v78
	v_fmac_f32_e32 v167, v80, v80
	v_add_f32_e32 v170, v166, v167
	v_lshlrev_b32_e32 v166, 16, v168
	v_and_b32_e32 v167, 0xffff0000, v168
	v_lshlrev_b32_e32 v168, 16, v169
	v_and_b32_e32 v169, 0xffff0000, v169
	v_pk_fma_f32 v[76:77], v[76:77], 0.5, v[168:169] op_sel_hi:[1,0,1]
	v_pk_fma_f32 v[74:75], v[74:75], 0.5, v[166:167] op_sel_hi:[1,0,1]
	v_mul_f32_e32 v167, v77, v77
	v_mul_f32_e32 v166, v75, v75
	v_fmac_f32_e32 v166, v74, v74
	v_fmac_f32_e32 v167, v76, v76
	v_add_f32_e32 v166, v166, v167
	v_add_f32_e32 v168, v170, v166
	s_waitcnt vmcnt(8)
	v_lshlrev_b32_e32 v166, 16, v162
	v_and_b32_e32 v167, 0xffff0000, v162
	v_lshlrev_b32_e32 v162, 16, v163
	v_and_b32_e32 v163, 0xffff0000, v163
	v_pk_fma_f32 v[72:73], v[72:73], 0.5, v[162:163] op_sel_hi:[1,0,1]
	v_pk_fma_f32 v[70:71], v[70:71], 0.5, v[166:167] op_sel_hi:[1,0,1]
	v_mul_f32_e32 v163, v73, v73
	v_mul_f32_e32 v162, v71, v71
	v_fmac_f32_e32 v162, v70, v70
	v_fmac_f32_e32 v163, v72, v72
	v_add_f32_e32 v162, v162, v163
	v_add_f32_e32 v166, v168, v162
	v_lshlrev_b32_e32 v162, 16, v164
	v_and_b32_e32 v163, 0xffff0000, v164
	v_lshlrev_b32_e32 v164, 16, v165
	v_and_b32_e32 v165, 0xffff0000, v165
	v_pk_fma_f32 v[64:65], v[64:65], 0.5, v[164:165] op_sel_hi:[1,0,1]
	v_pk_fma_f32 v[62:63], v[62:63], 0.5, v[162:163] op_sel_hi:[1,0,1]
	v_mul_f32_e32 v163, v65, v65
	v_mul_f32_e32 v162, v63, v63
	v_fmac_f32_e32 v162, v62, v62
	v_fmac_f32_e32 v163, v64, v64
	v_add_f32_e32 v162, v162, v163
	v_add_f32_e32 v162, v162, v166
	v_mov_b32_e32 v163, v162
	s_nop 1
	v_permlane16_swap_b32_e32 v162, v163
	s_waitcnt lgkmcnt(0)
	v_add_f32_e32 v162, v162, v163
	v_mov_b32_e32 v163, v162
	s_nop 1
	v_permlane32_swap_b32_e32 v162, v163
	s_and_saveexec_b64 s[58:59], vcc
	s_cbranch_execz .LBB0_2172
	s_waitcnt lgkmcnt(0)
	v_add_f32_e32 v162, v162, v163
	ds_write_b32 v186, v162 offset:768
.LBB0_2172:
	s_or_b64 exec, exec, s[58:59]
	s_waitcnt vmcnt(7)
	v_lshlrev_b32_e32 v162, 16, v158
	s_waitcnt lgkmcnt(0)
	v_and_b32_e32 v163, 0xffff0000, v158
	v_lshlrev_b32_e32 v158, 16, v159
	v_and_b32_e32 v159, 0xffff0000, v159
	v_pk_fma_f32 v[68:69], v[68:69], 0.5, v[158:159] op_sel_hi:[1,0,1]
	v_pk_fma_f32 v[66:67], v[66:67], 0.5, v[162:163] op_sel_hi:[1,0,1]
	v_mul_f32_e32 v159, v69, v69
	v_mul_f32_e32 v158, v67, v67
	v_fmac_f32_e32 v158, v66, v66
	v_fmac_f32_e32 v159, v68, v68
	v_add_f32_e32 v162, v158, v159
	v_lshlrev_b32_e32 v158, 16, v160
	v_and_b32_e32 v159, 0xffff0000, v160
	v_lshlrev_b32_e32 v160, 16, v161
	v_and_b32_e32 v161, 0xffff0000, v161
	v_pk_fma_f32 v[60:61], v[60:61], 0.5, v[160:161] op_sel_hi:[1,0,1]
	v_pk_fma_f32 v[58:59], v[58:59], 0.5, v[158:159] op_sel_hi:[1,0,1]
	v_mul_f32_e32 v159, v61, v61
	v_mul_f32_e32 v158, v59, v59
	v_fmac_f32_e32 v158, v58, v58
	v_fmac_f32_e32 v159, v60, v60
	v_add_f32_e32 v158, v158, v159
	v_add_f32_e32 v160, v162, v158
	s_waitcnt vmcnt(6)
	v_lshlrev_b32_e32 v158, 16, v154
	v_and_b32_e32 v159, 0xffff0000, v154
	v_lshlrev_b32_e32 v154, 16, v155
	v_and_b32_e32 v155, 0xffff0000, v155
	v_pk_fma_f32 v[56:57], v[56:57], 0.5, v[154:155] op_sel_hi:[1,0,1]
	v_pk_fma_f32 v[54:55], v[54:55], 0.5, v[158:159] op_sel_hi:[1,0,1]
	v_mul_f32_e32 v155, v57, v57
	v_mul_f32_e32 v154, v55, v55
	v_fmac_f32_e32 v154, v54, v54
	v_fmac_f32_e32 v155, v56, v56
	v_add_f32_e32 v154, v154, v155
	v_add_f32_e32 v158, v160, v154
	v_lshlrev_b32_e32 v154, 16, v156
	v_and_b32_e32 v155, 0xffff0000, v156
	v_lshlrev_b32_e32 v156, 16, v157
	v_and_b32_e32 v157, 0xffff0000, v157
	v_pk_fma_f32 v[52:53], v[52:53], 0.5, v[156:157] op_sel_hi:[1,0,1]
	v_pk_fma_f32 v[50:51], v[50:51], 0.5, v[154:155] op_sel_hi:[1,0,1]
	v_mul_f32_e32 v155, v53, v53
	v_mul_f32_e32 v154, v51, v51
	v_fmac_f32_e32 v154, v50, v50
	v_fmac_f32_e32 v155, v52, v52
	v_add_f32_e32 v154, v154, v155
	v_add_f32_e32 v154, v154, v158
	v_mov_b32_e32 v155, v154
	s_nop 1
	v_permlane16_swap_b32_e32 v154, v155
	s_waitcnt lgkmcnt(0)
	v_add_f32_e32 v154, v154, v155
	v_mov_b32_e32 v155, v154
	s_nop 1
	v_permlane32_swap_b32_e32 v154, v155
	s_and_saveexec_b64 s[58:59], vcc
	s_cbranch_execz .LBB0_2174
	s_waitcnt lgkmcnt(0)
	v_add_f32_e32 v154, v154, v155
	ds_write_b32 v186, v154 offset:2048
.LBB0_2174:
	s_or_b64 exec, exec, s[58:59]
	s_waitcnt vmcnt(5)
	v_lshlrev_b32_e32 v154, 16, v150
	s_waitcnt lgkmcnt(0)
	v_and_b32_e32 v155, 0xffff0000, v150
	v_lshlrev_b32_e32 v150, 16, v151
	v_and_b32_e32 v151, 0xffff0000, v151
	v_pk_fma_f32 v[48:49], v[48:49], 0.5, v[150:151] op_sel_hi:[1,0,1]
	v_pk_fma_f32 v[46:47], v[46:47], 0.5, v[154:155] op_sel_hi:[1,0,1]
	v_mul_f32_e32 v151, v49, v49
	v_mul_f32_e32 v150, v47, v47
	v_fmac_f32_e32 v150, v46, v46
	v_fmac_f32_e32 v151, v48, v48
	v_add_f32_e32 v154, v150, v151
	v_lshlrev_b32_e32 v150, 16, v152
	v_and_b32_e32 v151, 0xffff0000, v152
	v_lshlrev_b32_e32 v152, 16, v153
	v_and_b32_e32 v153, 0xffff0000, v153
	v_pk_fma_f32 v[44:45], v[44:45], 0.5, v[152:153] op_sel_hi:[1,0,1]
	v_pk_fma_f32 v[42:43], v[42:43], 0.5, v[150:151] op_sel_hi:[1,0,1]
	v_mul_f32_e32 v151, v45, v45
	v_mul_f32_e32 v150, v43, v43
	v_fmac_f32_e32 v150, v42, v42
	v_fmac_f32_e32 v151, v44, v44
	v_add_f32_e32 v150, v150, v151
	v_add_f32_e32 v152, v154, v150
	s_waitcnt vmcnt(4)
	v_lshlrev_b32_e32 v150, 16, v142
	v_and_b32_e32 v151, 0xffff0000, v142
	v_lshlrev_b32_e32 v142, 16, v143
	v_and_b32_e32 v143, 0xffff0000, v143
	v_pk_fma_f32 v[40:41], v[40:41], 0.5, v[142:143] op_sel_hi:[1,0,1]
	v_pk_fma_f32 v[38:39], v[38:39], 0.5, v[150:151] op_sel_hi:[1,0,1]
	v_mul_f32_e32 v143, v41, v41
	v_mul_f32_e32 v142, v39, v39
	v_fmac_f32_e32 v142, v38, v38
	v_fmac_f32_e32 v143, v40, v40
	v_add_f32_e32 v142, v142, v143
	v_add_f32_e32 v150, v152, v142
	v_lshlrev_b32_e32 v142, 16, v144
	v_and_b32_e32 v143, 0xffff0000, v144
	v_lshlrev_b32_e32 v144, 16, v145
	v_and_b32_e32 v145, 0xffff0000, v145
	v_pk_fma_f32 v[36:37], v[36:37], 0.5, v[144:145] op_sel_hi:[1,0,1]
	v_pk_fma_f32 v[34:35], v[34:35], 0.5, v[142:143] op_sel_hi:[1,0,1]
	v_mul_f32_e32 v143, v37, v37
	v_mul_f32_e32 v142, v35, v35
	v_fmac_f32_e32 v142, v34, v34
	v_fmac_f32_e32 v143, v36, v36
	v_add_f32_e32 v142, v142, v143
	v_add_f32_e32 v142, v142, v150
	v_mov_b32_e32 v143, v142
	s_nop 1
	v_permlane16_swap_b32_e32 v142, v143
	s_waitcnt lgkmcnt(0)
	v_add_f32_e32 v142, v142, v143
	v_mov_b32_e32 v143, v142
	s_nop 1
	v_permlane32_swap_b32_e32 v142, v143
	s_and_saveexec_b64 s[58:59], vcc
	s_cbranch_execz .LBB0_2176
	s_waitcnt lgkmcnt(0)
	v_add_f32_e32 v142, v142, v143
	ds_write_b32 v186, v142 offset:2304
.LBB0_2176:
	s_or_b64 exec, exec, s[58:59]
	s_waitcnt vmcnt(3)
	v_lshlrev_b32_e32 v142, 16, v134
	s_waitcnt lgkmcnt(0)
	v_and_b32_e32 v143, 0xffff0000, v134
	v_lshlrev_b32_e32 v134, 16, v135
	v_and_b32_e32 v135, 0xffff0000, v135
	v_pk_fma_f32 v[32:33], v[32:33], 0.5, v[134:135] op_sel_hi:[1,0,1]
	v_pk_fma_f32 v[30:31], v[30:31], 0.5, v[142:143] op_sel_hi:[1,0,1]
	v_mul_f32_e32 v135, v33, v33
	v_mul_f32_e32 v134, v31, v31
	v_fmac_f32_e32 v134, v30, v30
	v_fmac_f32_e32 v135, v32, v32
	v_add_f32_e32 v142, v134, v135
	v_lshlrev_b32_e32 v134, 16, v136
	v_and_b32_e32 v135, 0xffff0000, v136
	v_lshlrev_b32_e32 v136, 16, v137
	v_and_b32_e32 v137, 0xffff0000, v137
	v_pk_fma_f32 v[28:29], v[28:29], 0.5, v[136:137] op_sel_hi:[1,0,1]
	v_pk_fma_f32 v[26:27], v[26:27], 0.5, v[134:135] op_sel_hi:[1,0,1]
	v_mul_f32_e32 v135, v29, v29
	v_mul_f32_e32 v134, v27, v27
	v_fmac_f32_e32 v134, v26, v26
	v_fmac_f32_e32 v135, v28, v28
	v_add_f32_e32 v134, v134, v135
	v_add_f32_e32 v136, v142, v134
	s_waitcnt vmcnt(2)
	v_lshlrev_b32_e32 v134, 16, v130
	v_and_b32_e32 v135, 0xffff0000, v130
	v_lshlrev_b32_e32 v130, 16, v131
	v_and_b32_e32 v131, 0xffff0000, v131
	v_pk_fma_f32 v[24:25], v[24:25], 0.5, v[130:131] op_sel_hi:[1,0,1]
	v_pk_fma_f32 v[22:23], v[22:23], 0.5, v[134:135] op_sel_hi:[1,0,1]
	v_mul_f32_e32 v131, v25, v25
	v_mul_f32_e32 v130, v23, v23
	v_fmac_f32_e32 v130, v22, v22
	v_fmac_f32_e32 v131, v24, v24
	v_add_f32_e32 v130, v130, v131
	v_add_f32_e32 v134, v136, v130
	v_lshlrev_b32_e32 v130, 16, v132
	v_and_b32_e32 v131, 0xffff0000, v132
	v_lshlrev_b32_e32 v132, 16, v133
	v_and_b32_e32 v133, 0xffff0000, v133
	v_pk_fma_f32 v[20:21], v[20:21], 0.5, v[132:133] op_sel_hi:[1,0,1]
	v_pk_fma_f32 v[18:19], v[18:19], 0.5, v[130:131] op_sel_hi:[1,0,1]
	v_mul_f32_e32 v131, v21, v21
	v_mul_f32_e32 v130, v19, v19
	v_fmac_f32_e32 v130, v18, v18
	v_fmac_f32_e32 v131, v20, v20
	v_add_f32_e32 v130, v130, v131
	v_add_f32_e32 v130, v130, v134
	v_mov_b32_e32 v131, v130
	s_nop 1
	v_permlane16_swap_b32_e32 v130, v131
	s_waitcnt lgkmcnt(0)
	v_add_f32_e32 v130, v130, v131
	v_mov_b32_e32 v131, v130
	s_nop 1
	v_permlane32_swap_b32_e32 v130, v131
	s_and_saveexec_b64 s[58:59], vcc
	s_cbranch_execz .LBB0_2178
	s_waitcnt lgkmcnt(0)
	v_add_f32_e32 v130, v130, v131
	ds_write_b32 v186, v130 offset:2560
.LBB0_2178:
	s_or_b64 exec, exec, s[58:59]
	s_waitcnt vmcnt(1)
	v_lshlrev_b32_e32 v130, 16, v146
	s_waitcnt lgkmcnt(0)
	v_and_b32_e32 v131, 0xffff0000, v146
	v_lshlrev_b32_e32 v132, 16, v147
	v_and_b32_e32 v133, 0xffff0000, v147
	v_pk_fma_f32 v[132:133], v[16:17], 0.5, v[132:133] op_sel_hi:[1,0,1]
	v_pk_fma_f32 v[130:131], v[14:15], 0.5, v[130:131] op_sel_hi:[1,0,1]
	v_mul_f32_e32 v15, v133, v133
	v_mul_f32_e32 v14, v131, v131
	v_fmac_f32_e32 v14, v130, v130
	v_fmac_f32_e32 v15, v132, v132
	v_add_f32_e32 v142, v14, v15
	v_lshlrev_b32_e32 v14, 16, v148
	v_and_b32_e32 v15, 0xffff0000, v148
	v_lshlrev_b32_e32 v16, 16, v149
	v_and_b32_e32 v17, 0xffff0000, v149
	v_pk_fma_f32 v[136:137], v[12:13], 0.5, v[16:17] op_sel_hi:[1,0,1]
	v_pk_fma_f32 v[134:135], v[10:11], 0.5, v[14:15] op_sel_hi:[1,0,1]
	v_mul_f32_e32 v11, v137, v137
	v_mul_f32_e32 v10, v135, v135
	v_fmac_f32_e32 v10, v134, v134
	v_fmac_f32_e32 v11, v136, v136
	v_add_f32_e32 v10, v10, v11
	v_add_f32_e32 v14, v142, v10
	s_waitcnt vmcnt(0)
	v_lshlrev_b32_e32 v10, 16, v138
	v_and_b32_e32 v11, 0xffff0000, v138
	v_lshlrev_b32_e32 v12, 16, v139
	v_and_b32_e32 v13, 0xffff0000, v139
	v_pk_fma_f32 v[148:149], v[8:9], 0.5, v[12:13] op_sel_hi:[1,0,1]
	v_pk_fma_f32 v[146:147], v[6:7], 0.5, v[10:11] op_sel_hi:[1,0,1]
	v_mul_f32_e32 v7, v149, v149
	v_mul_f32_e32 v6, v147, v147
	v_fmac_f32_e32 v6, v146, v146
	v_fmac_f32_e32 v7, v148, v148
	v_add_f32_e32 v6, v6, v7
	v_add_f32_e32 v10, v14, v6
	v_lshlrev_b32_e32 v6, 16, v140
	v_and_b32_e32 v7, 0xffff0000, v140
	v_lshlrev_b32_e32 v8, 16, v141
	v_and_b32_e32 v9, 0xffff0000, v141
	v_pk_fma_f32 v[156:157], v[4:5], 0.5, v[8:9] op_sel_hi:[1,0,1]
	v_pk_fma_f32 v[154:155], v[2:3], 0.5, v[6:7] op_sel_hi:[1,0,1]
	v_mul_f32_e32 v3, v157, v157
	v_mul_f32_e32 v2, v155, v155
	v_fmac_f32_e32 v2, v154, v154
	v_fmac_f32_e32 v3, v156, v156
	v_add_f32_e32 v2, v2, v3
	v_add_f32_e32 v2, v2, v10
	v_mov_b32_e32 v3, v2
	s_nop 1
	v_permlane16_swap_b32_e32 v2, v3
	s_waitcnt lgkmcnt(0)
	v_add_f32_e32 v2, v2, v3
	v_mov_b32_e32 v3, v2
	s_nop 1
	v_permlane32_swap_b32_e32 v2, v3
	s_and_saveexec_b64 s[58:59], vcc
	s_cbranch_execz .LBB0_2180
	s_waitcnt lgkmcnt(0)
	v_add_f32_e32 v2, v2, v3
	ds_write_b32 v186, v2 offset:2816
